# POST tile epilogue hand-written: all global loads of a 32-token half issued together, per-channel tables staged once per block in LDS (static LDS +2560 B)
# speedup vs baseline: 1.0284x; 1.0005x over previous
; DI int TIDX() { int t = threadIdx.x; asm volatile("" : "+v"(t)); return t; }
; DI int BIDX() { int b = blockIdx.x; asm volatile("" : "+s"(b)); return b; }
; DI void gemm_tile_deep(const h16* __restrict__ A, int lda, const h16* __restrict__ B, int ldb, int K, f32x16 (&acc)[2][2], h16* sm) {
;   const int tid = TIDX(), lane = tid & 63, w = tid >> 6, wm = w >> 1, wn = w & 1, r = lane & 31, hh = lane >> 5;
;   const unsigned ao = (unsigned)(tid >> 3) * (unsigned)lda + (unsigned)(tid & 7) * 8u;
;   const unsigned bo = (unsigned)(tid >> 3) * (unsigned)ldb + (unsigned)(tid & 7) * 8u;
;   const h16* ag = A;
;   const h16* bg = B;
;   u32x4 ra0[4], rb0[4], ra1[4], rb1[4];
; #pragma unroll
;   for (int i = 0; i < 4; ++i) {
;     ra0[i] = *(const u32x4*)(ag + (ao + (unsigned)i * 32u * (unsigned)lda));
;     rb0[i] = *(const u32x4*)(bg + (bo + (unsigned)i * 32u * (unsigned)ldb));
;   }
;   ag += 64; bg += 64;
; #pragma unroll
;   for (int i = 0; i < 4; ++i) {
;     ra1[i] = *(const u32x4*)(ag + (ao + (unsigned)i * 32u * (unsigned)lda));
;     rb1[i] = *(const u32x4*)(bg + (bo + (unsigned)i * 32u * (unsigned)ldb));
;   }
;   const int nk = K >> 6;
;   const int wofs = (tid >> 3) * LSTR + (tid & 7) * 8;
; DI void phase_post(const P& p, int l, char* smem) {
;     ...
;   const float* lng = p.in[I_LNG] + l * 512;
;   const float* lnb = p.in[I_LNB] + l * 512;
;   const float* cvp = p.in[I_CONV] + (size_t)l * 3 * 1536 + 1024;
;   const int ntok = (l == 1) ? 256 : 272;
;   const int nt = 4 * ntok;
;   const int lane = TIDX() & 63, w = TIDX() >> 6, wm = w >> 1, wn = w & 1, hh = lane >> 5;
;   for (int t = BIDX(); t < nt; t += gridDim.x) {
;     const int m0 = (t & 3) * 128, n0 = (t >> 2) * 128;
;     f32x16 acc[2][2];
;     zero_acc(acc);
;     gemm_tile_deep(W + (size_t)m0 * 128, 128, lora + (size_t)n0 * 384 + 256, 384, 128, acc, (h16*)smem);
.LBB0_119:
	s_andn2_b64 vcc, exec, s[0:1]
	s_cbranch_vccnz .LBB0_161
	s_and_b64 s[0:1], s[70:71], exec
	s_movk_i32 s0, 0x440
	s_cselect_b32 s18, s0, 0x400
	v_mov_b32_e32 v0, v203
	v_mov_b32_e32 v2, v203
	s_mov_b32 s19, s31
	s_cmp_ge_i32 s19, s18
	s_cbranch_scc1 .LBB0_155
	s_add_u32 s46, s48, 0xda0000
	s_addc_u32 s47, s49, 0
	s_add_u32 s4, s48, 0x756c000
	s_addc_u32 s5, s49, 0
	s_add_u32 s6, s48, 0x316c000
	s_addc_u32 s7, s49, 0
	s_add_u32 s8, s48, 0x536c000
	s_addc_u32 s9, s49, 0
	s_add_u32 s10, s48, 0x2d2c000
	s_addc_u32 s11, s49, 0
	v_readlane_b32 s48, v253, 4
	s_lshl_b32 s0, s78, 11
	v_readlane_b32 s52, v253, 8
	v_readlane_b32 s53, v253, 9
	s_add_u32 s12, s52, s0
	v_readlane_b32 s54, v253, 10
	s_addc_u32 s13, s53, 0
	v_readlane_b32 s49, v253, 5
	v_readlane_b32 s50, v253, 6
	v_readlane_b32 s51, v253, 7
	v_readlane_b32 s55, v253, 11
	v_readlane_b32 s56, v253, 12
	v_readlane_b32 s57, v253, 13
	v_readlane_b32 s58, v253, 14
	v_readlane_b32 s59, v253, 15
	v_readlane_b32 s60, v253, 16
	v_readlane_b32 s61, v253, 17
	v_readlane_b32 s62, v253, 18
	v_readlane_b32 s63, v253, 19
	s_add_u32 s14, s54, s0
	s_addc_u32 s15, s55, 0
	v_readlane_b32 s48, v252, 33
	s_mul_i32 s0, s78, 0x4800
	v_readlane_b32 s50, v252, 35
	v_readlane_b32 s51, v252, 36
	s_add_u32 s0, s50, s0
	v_readlane_b32 s49, v252, 34
	s_addc_u32 s1, s51, 0
	v_ashrrev_i32_e32 v3, 1, v2
	v_readlane_b32 s48, v255, 14
	s_add_u32 s16, s0, 0x1000
	v_and_b32_e32 v124, 0xffffffc0, v3
	v_and_b32_e32 v3, 31, v0
	v_lshrrev_b32_e32 v0, 3, v0
	v_readlane_b32 s49, v255, 15
	s_addc_u32 s17, s1, 0
	v_and_or_b32 v125, v2, 64, v3
	v_and_b32_e32 v126, 4, v0
	s_lshl_b32 s50, s19, 5
	s_lshl_b32 s51, s19, 7
	v_readlane_b32 s52, v252, 37
	v_readlane_b32 s53, v252, 38
	v_readlane_b32 s54, v252, 39
	v_readlane_b32 s55, v252, 40
	v_readlane_b32 s56, v252, 41
	v_readlane_b32 s57, v252, 42
	v_readlane_b32 s58, v252, 43
	v_readlane_b32 s59, v252, 44
	v_readlane_b32 s60, v252, 45
	v_readlane_b32 s61, v252, 46
	v_readlane_b32 s62, v252, 47
	v_readlane_b32 s63, v252, 48
	v_and_b32_e32 v0, 0x7f, v203
	s_and_b32 s2, s31, 3
	s_lshl_b32 s2, s2, 9
	v_lshl_add_u32 v0, v0, 2, s2
	global_load_dword v66, v0, s[16:17]
	v_add_u32_e32 v73, 0x1800, v0
	global_load_dword v67, v73, s[16:17]
	v_add_u32_e32 v70, 0x3000, v0
	global_load_dword v68, v70, s[16:17]
	global_load_dword v69, v0, s[12:13]
	global_load_dword v71, v0, s[14:15]
	v_and_b32_e32 v72, 0x7f, v203
	v_lshlrev_b32_e32 v72, 2, v72
	v_add_u32_e32 v72, 0x12010, v72
	s_waitcnt vmcnt(0)
	ds_write_b32 v72, v66
	ds_write_b32 v72, v67 offset:512
	ds_write_b32 v72, v68 offset:1024
	ds_write_b32 v72, v69 offset:1536
	ds_write_b32 v72, v71 offset:2048
	s_waitcnt lgkmcnt(0)
	s_barrier
	s_branch .LBB0_123
.LBB0_123:
	s_and_b32 s1, s51, 0x180
	s_and_b32 s0, s50, 0xffffff80
	s_lshl_b32 s20, s1, 8
	s_add_u32 s20, s46, s20
	s_waitcnt vmcnt(3)
	v_mov_b32_e32 v50, v203
	s_addc_u32 s21, s47, 0
	s_mul_i32 s23, s0, 0x300
	s_movk_i32 s2, 0x180
	v_ashrrev_i32_e32 v51, 3, v50
	v_lshlrev_b32_e32 v0, 3, v50
	s_mul_hi_i32 s22, s0, 0x300
	s_add_u32 s24, s48, s23
	v_and_b32_e32 v52, 56, v0
	v_mul_lo_u32 v2, v51, s2
	s_addc_u32 s25, s49, s22
	v_or_b32_e32 v2, v2, v52
	s_add_u32 s22, s24, 0xdb6c200
	v_lshl_or_b32 v0, v51, 7, v52
	v_mov_b32_e32 v3, v1
	v_add_u32_e32 v4, 0x3000, v2
	v_mov_b32_e32 v5, v1
	v_add_u32_e32 v8, 0x6000, v2
	v_mov_b32_e32 v9, v1
	v_add_u32_e32 v14, 0x9000, v2
	v_mov_b32_e32 v15, v1
	s_addc_u32 s23, s25, 0
	v_add_u32_e32 v10, 0x1000, v0
	v_mov_b32_e32 v11, v1
	v_add_u32_e32 v6, 0x2000, v0
	v_mov_b32_e32 v7, v1
	v_lshlrev_b64 v[34:35], 1, v[14:15]
	v_lshlrev_b64 v[38:39], 1, v[8:9]
	v_lshlrev_b64 v[42:43], 1, v[4:5]
	v_lshlrev_b64 v[44:45], 1, v[2:3]
	v_add_u32_e32 v12, 0x3000, v0
	v_mov_b32_e32 v13, v1
	v_lshl_add_u64 v[40:41], v[6:7], 1, s[20:21]
	v_lshl_add_u64 v[46:47], v[0:1], 1, s[20:21]
	v_lshl_add_u64 v[26:27], s[22:23], 0, v[34:35]
	v_lshl_add_u64 v[30:31], s[22:23], 0, v[38:39]
	v_lshl_add_u64 v[18:19], s[22:23], 0, v[42:43]
	v_lshl_add_u64 v[22:23], s[22:23], 0, v[44:45]
	v_lshl_add_u64 v[48:49], v[10:11], 1, s[20:21]
	v_lshl_add_u64 v[36:37], v[12:13], 1, s[20:21]
	global_load_dwordx4 v[2:5], v[40:41], off
	global_load_dwordx4 v[6:9], v[46:47], off
	global_load_dwordx4 v[10:13], v[48:49], off
	global_load_dwordx4 v[14:17], v[36:37], off
	s_nop 0
	global_load_dwordx4 v[18:21], v[18:19], off
	s_nop 0
	global_load_dwordx4 v[22:25], v[22:23], off
	s_nop 0
	global_load_dwordx4 v[26:29], v[26:27], off
	s_nop 0
	global_load_dwordx4 v[30:33], v[30:31], off
	s_add_u32 s24, s24, 0xdb6c280
	s_addc_u32 s25, s25, 0
	v_lshl_add_u64 v[34:35], s[24:25], 0, v[34:35]
	global_load_dwordx4 v[66:69], v[34:35], off
	global_load_dwordx4 v[70:73], v[40:41], off offset:128
	v_lshl_add_u64 v[34:35], s[24:25], 0, v[42:43]
	global_load_dwordx4 v[74:77], v[34:35], off
	global_load_dwordx4 v[78:81], v[46:47], off offset:128
	v_lshl_add_u64 v[34:35], s[24:25], 0, v[38:39]
	global_load_dwordx4 v[82:85], v[36:37], off offset:128
	global_load_dwordx4 v[86:89], v[34:35], off
	v_lshl_add_u64 v[34:35], s[24:25], 0, v[44:45]
	global_load_dwordx4 v[90:93], v[48:49], off offset:128
	global_load_dwordx4 v[94:97], v[34:35], off
	s_movk_i32 s2, 0x48
	v_and_b32_e32 v0, 31, v50
	v_lshrrev_b32_e32 v34, 1, v50
	v_mul_lo_u32 v36, v51, s2
	s_mov_b32 s2, 0xfffffc0
	v_and_b32_e32 v35, 0x5f, v50
	v_and_or_b32 v37, v34, s2, v0
	v_and_b32_e32 v0, 16, v34
	v_mul_u32_u24_e32 v34, 0x48, v35
	v_add_lshl_u32 v127, v36, v52, 1
	s_waitcnt vmcnt(16)
	v_mad_u64_u32 v[122:123], s[20:21], v37, s28, v[0:1]
	v_lshl_add_u32 v0, v34, 1, v0
	v_add_u32_e32 v123, 0xd800, v127
	s_waitcnt vmcnt(14)
	ds_write_b128 v127, v[6:9]
	ds_write_b128 v127, v[2:5] offset:9216
	s_waitcnt vmcnt(13)
	ds_write_b128 v127, v[10:13] offset:4608
	s_waitcnt vmcnt(12)
	ds_write_b128 v127, v[14:17] offset:13824
	s_waitcnt vmcnt(10)
	ds_write_b128 v127, v[22:25] offset:18432
	ds_write_b128 v127, v[18:21] offset:23040
	s_waitcnt vmcnt(8)
	ds_write_b128 v127, v[30:33] offset:27648
	ds_write_b128 v127, v[26:29] offset:32256
	s_waitcnt lgkmcnt(0)
	s_barrier
; #define L(ph, l, hf) hipLaunchKernelGGL(k_phase<ph>, dim3(G), dim3(256), 0, stream, p, l, hf)
; DI void gemm_tile_deep(const h16* __restrict__ A, int lda, const h16* __restrict__ B, int ldb, int K, f32x16 (&acc)[2][2], h16* sm) {
;     ...
;   for (int kt = 0; kt < nk; kt += 2) {
;     DEEP_HALF(ra0, rb0, 0, kt)
;     DEEP_HALF(ra1, rb1, 1, kt + 1)
;   }
;     ...
;   __syncthreads();
; DI void phase_post(const P& p, int l, char* smem) {
;     ...
;     for (int ni = 0; ni < 2; ++ni) {
;       const int row = n0 + wn * 64 + ni * 32 + (lane & 31);
;       const bool lat = row < TL;
;       const int pos = lat ? (row & 4095) : ((row - TL) & 255);
;       const int L = lat ? 4096 : 256;
;       float y[2][16];
;       float sum = 0.f;
; #pragma unroll
;       for (int mi = 0; mi < 2; ++mi)
; #pragma unroll
;         for (int g = 0; g < 4; ++g) {
;           const int cb_ = m0 + wm * 64 + mi * 32 + 8 * g + 4 * hh;
;           h16x4 f = *(const h16x4*)(sof + (size_t)row * 512 + cb_), bk = *(const h16x4*)(sob + (size_t)row * 512 + cb_);
	ds_read_b128 v[2:5], v122
	ds_read_b128 v[6:9], v122 offset:4608
	ds_read_b128 v[10:13], v0 offset:18432
	ds_read_b128 v[14:17], v0 offset:23040
	s_waitcnt lgkmcnt(1)
	v_mfma_f32_32x32x16_f16 v[50:65], v[2:5], v[10:13], 0
	ds_read_b128 v[98:101], v122 offset:32
	ds_read_b128 v[102:105], v122 offset:4640
	ds_read_b128 v[106:109], v0 offset:18464
	ds_read_b128 v[110:113], v0 offset:23072
	s_waitcnt lgkmcnt(4)
	v_mfma_f32_32x32x16_f16 v[18:33], v[2:5], v[14:17], 0
	v_mfma_f32_32x32x16_f16 v[34:49], v[6:9], v[10:13], 0
	v_mfma_f32_32x32x16_f16 v[2:17], v[6:9], v[14:17], 0
	s_waitcnt lgkmcnt(1)
	v_mfma_f32_32x32x16_f16 v[50:65], v[98:101], v[106:109], v[50:65]
	s_waitcnt lgkmcnt(0)
	v_mfma_f32_32x32x16_f16 v[18:33], v[98:101], v[110:113], v[18:33]
	v_mfma_f32_32x32x16_f16 v[34:49], v[102:105], v[106:109], v[34:49]
	ds_read_b128 v[98:101], v122 offset:64
	ds_read_b128 v[106:109], v122 offset:4672
	ds_read_b128 v[114:117], v0 offset:18496
	ds_read_b128 v[118:121], v0 offset:23104
	v_mfma_f32_32x32x16_f16 v[2:17], v[102:105], v[110:113], v[2:17]
	s_waitcnt lgkmcnt(1)
	v_mfma_f32_32x32x16_f16 v[50:65], v[98:101], v[114:117], v[50:65]
	s_waitcnt lgkmcnt(0)
	v_mfma_f32_32x32x16_f16 v[18:33], v[98:101], v[118:121], v[18:33]
	v_mfma_f32_32x32x16_f16 v[34:49], v[106:109], v[114:117], v[34:49]
	ds_read_b128 v[98:101], v122 offset:96
	ds_read_b128 v[102:105], v122 offset:4704
	ds_read_b128 v[110:113], v0 offset:18528
	ds_read_b128 v[114:117], v0 offset:23136
	v_mfma_f32_32x32x16_f16 v[2:17], v[106:109], v[118:121], v[2:17]
	s_waitcnt lgkmcnt(1)
	v_mfma_f32_32x32x16_f16 v[50:65], v[98:101], v[110:113], v[50:65]
	s_waitcnt lgkmcnt(0)
	v_mfma_f32_32x32x16_f16 v[18:33], v[98:101], v[114:117], v[18:33]
	v_mfma_f32_32x32x16_f16 v[34:49], v[102:105], v[110:113], v[34:49]
	v_mfma_f32_32x32x16_f16 v[2:17], v[102:105], v[114:117], v[2:17]
	s_waitcnt vmcnt(4)
	ds_write_b128 v127, v[78:81] offset:36864
	s_waitcnt vmcnt(0)
	ds_write_b128 v127, v[94:97] offset:55296
	ds_write_b128 v127, v[90:93] offset:41472
	ds_write_b128 v127, v[74:77] offset:59904
	ds_write_b128 v127, v[70:73] offset:46080
	ds_write_b128 v127, v[86:89] offset:64512
	ds_write_b128 v127, v[82:85] offset:50688
	ds_write_b128 v123, v[66:69] offset:13824
	s_waitcnt lgkmcnt(0)
	s_barrier
	ds_read_b128 v[66:69], v122 offset:36864
	ds_read_b128 v[70:73], v122 offset:41472
	ds_read_b128 v[74:77], v0 offset:55296
	ds_read_b128 v[78:81], v0 offset:59904
	s_waitcnt lgkmcnt(1)
	v_mfma_f32_32x32x16_f16 v[50:65], v[66:69], v[74:77], v[50:65]
	s_waitcnt lgkmcnt(0)
	v_mfma_f32_32x32x16_f16 v[18:33], v[66:69], v[78:81], v[18:33]
	v_mfma_f32_32x32x16_f16 v[34:49], v[70:73], v[74:77], v[34:49]
	ds_read_b128 v[66:69], v122 offset:36896
	ds_read_b128 v[74:77], v122 offset:41504
	ds_read_b128 v[82:85], v0 offset:55328
	ds_read_b128 v[86:89], v0 offset:59936
	v_mfma_f32_32x32x16_f16 v[2:17], v[70:73], v[78:81], v[2:17]
	s_waitcnt lgkmcnt(1)
	v_mfma_f32_32x32x16_f16 v[50:65], v[66:69], v[82:85], v[50:65]
	s_waitcnt lgkmcnt(0)
	v_mfma_f32_32x32x16_f16 v[18:33], v[66:69], v[86:89], v[18:33]
	v_mfma_f32_32x32x16_f16 v[34:49], v[74:77], v[82:85], v[34:49]
	ds_read_b128 v[66:69], v122 offset:36928
	ds_read_b128 v[70:73], v122 offset:41536
	ds_read_b128 v[78:81], v0 offset:55360
	ds_read_b128 v[82:85], v0 offset:59968
	v_mfma_f32_32x32x16_f16 v[2:17], v[74:77], v[86:89], v[2:17]
	s_waitcnt lgkmcnt(1)
	v_mfma_f32_32x32x16_f16 v[50:65], v[66:69], v[78:81], v[50:65]
	s_waitcnt lgkmcnt(0)
	v_mfma_f32_32x32x16_f16 v[18:33], v[66:69], v[82:85], v[18:33]
	v_mfma_f32_32x32x16_f16 v[34:49], v[70:73], v[78:81], v[34:49]
	ds_read_b128 v[66:69], v122 offset:36960
	ds_read_b128 v[74:77], v122 offset:41568
	ds_read_b128 v[78:81], v0 offset:55392
	ds_read_b128 v[86:89], v0 offset:60000
	v_mfma_f32_32x32x16_f16 v[2:17], v[70:73], v[82:85], v[2:17]
	s_waitcnt lgkmcnt(1)
	v_mfma_f32_32x32x16_f16 v[50:65], v[66:69], v[78:81], v[50:65]
	s_waitcnt lgkmcnt(0)
	v_mfma_f32_32x32x16_f16 v[18:33], v[66:69], v[86:89], v[18:33]
	v_mfma_f32_32x32x16_f16 v[34:49], v[74:77], v[78:81], v[34:49]
	v_mfma_f32_32x32x16_f16 v[2:17], v[74:77], v[86:89], v[2:17]
	s_waitcnt vmcnt(0)
	s_barrier
	v_or_b32_e32 v114, s0, v125
	v_add_u32_e32 v115, s1, v124
	v_or_b32_e32 v115, v115, v126
	v_lshlrev_b32_e32 v116, 2, v124
	v_lshl_add_u32 v116, v126, 2, v116
	v_add_u32_e32 v116, 0x12010, v116
	s_lshr_b32 s2, s1, 6
	v_lshrrev_b32_e32 v117, 6, v124
	v_add_u32_e32 v117, s2, v117
	v_mov_b32_e32 v118, v114
	v_mov_b32_e32 v119, 0
	v_lshlrev_b64 v[246:247], 10, v[118:119]
	v_lshlrev_b32_e32 v0, 1, v115
	v_add_co_u32_e32 v246, vcc, v246, v0
	s_nop 1
	v_addc_co_u32_e32 v247, vcc, 0, v247, vcc
	v_lshl_add_u64 v[248:249], s[8:9], 0, v[246:247]
	v_lshl_add_u64 v[246:247], s[6:7], 0, v[246:247]
	s_movk_i32 s20, 0xc00
	v_mad_u64_u32 v[200:201], s[2:3], v118, s20, v[0:1]
	v_lshl_add_u64 v[200:201], s[4:5], 0, v[200:201]
	s_mov_b64 s[2:3], 0x1000
	v_lshl_add_u64 v[196:197], v[200:201], 0, s[2:3]
	v_lshl_add_u32 v198, v118, 3, v117
	v_mov_b32_e32 v199, 0
	v_lshlrev_b64 v[198:199], 2, v[198:199]
	v_lshl_add_u64 v[198:199], s[10:11], 0, v[198:199]
	global_load_dwordx2 v[66:67], v[246:247], off
	global_load_dwordx2 v[68:69], v[246:247], off offset:16
	global_load_dwordx2 v[70:71], v[246:247], off offset:32
	global_load_dwordx2 v[72:73], v[246:247], off offset:48
	global_load_dwordx2 v[74:75], v[246:247], off offset:64
	global_load_dwordx2 v[76:77], v[246:247], off offset:80
	global_load_dwordx2 v[78:79], v[246:247], off offset:96
	global_load_dwordx2 v[80:81], v[246:247], off offset:112
	global_load_dwordx2 v[82:83], v[248:249], off
	global_load_dwordx2 v[84:85], v[248:249], off offset:16
; #define L(ph, l, hf) hipLaunchKernelGGL(k_phase<ph>, dim3(G), dim3(256), 0, stream, p, l, hf)
; DI void phase_post(const P& p, int l, char* smem) {
;     ...
;       const int row = n0 + wn * 64 + ni * 32 + (lane & 31);
;       const bool lat = row < TL;
;       const int pos = lat ? (row & 4095) : ((row - TL) & 255);
;       const int L = lat ? 4096 : 256;
;       float y[2][16];
;       float sum = 0.f;
; #pragma unroll
;       for (int mi = 0; mi < 2; ++mi)
; #pragma unroll
;         for (int g = 0; g < 4; ++g) {
;           const int cb_ = m0 + wm * 64 + mi * 32 + 8 * g + 4 * hh;
;           h16x4 f = *(const h16x4*)(sof + (size_t)row * 512 + cb_), bk = *(const h16x4*)(sob + (size_t)row * 512 + cb_);
;           y[mi][4 * g + 0] = (float)f.x + (float)bk.x; y[mi][4 * g + 1] = (float)f.y + (float)bk.y;
;           y[mi][4 * g + 2] = (float)f.z + (float)bk.z; y[mi][4 * g + 3] = (float)f.w + (float)bk.w;
;           sum += y[mi][4 * g] + y[mi][4 * g + 1] + y[mi][4 * g + 2] + y[mi][4 * g + 3];
;         }
;       sum += shx(sum, 32);
;       const float mean = sum * (1.f / 64.f);
;       float vs = 0.f;
; #pragma unroll
;       for (int mi = 0; mi < 2; ++mi)
; #pragma unroll
;         for (int i = 0; i < 16; ++i) { const float dlt = y[mi][i] - mean; vs += dlt * dlt; }
;       vs += shx(vs, 32);
;       const float rstd = rsqrtf(vs * (1.f / 64.f) + 64e-5f);
;       const float bsum = bs[(size_t)row * 8 + head] + bs[((size_t)TA + row) * 8 + head];
; #pragma unroll
;       for (int mi = 0; mi < 2; ++mi)
; #pragma unroll
;         for (int g = 0; g < 4; ++g) {
;           const int cb_ = m0 + wm * 64 + mi * 32 + 8 * g + 4 * hh;
;           const h16* vp = rkv + (size_t)row * 1536 + 1024 + cb_;
;           h16x4 v1 = *(const h16x4*)vp, v0, v2;
;           v0.x = v0.y = v0.z = v0.w = (h16)0.f; v2 = v0;
;           if (pos > 0) v0 = *(const h16x4*)(vp - 1536);
;           if (pos < L - 1) v2 = *(const h16x4*)(vp + 1536);
	global_load_dwordx2 v[86:87], v[248:249], off offset:32
	global_load_dwordx2 v[88:89], v[248:249], off offset:48
	global_load_dwordx2 v[90:91], v[248:249], off offset:64
	global_load_dwordx2 v[92:93], v[248:249], off offset:80
	global_load_dwordx2 v[94:95], v[248:249], off offset:96
	global_load_dwordx2 v[96:97], v[248:249], off offset:112
	global_load_dword v194, v[198:199], off
	v_add_co_u32_e32 v198, vcc, 0x110000, v198
	s_nop 1
	v_addc_co_u32_e32 v199, vcc, 0, v199, vcc
	global_load_dword v195, v[198:199], off
	global_load_dwordx2 v[98:99], v[200:201], off offset:2048
	global_load_dwordx2 v[100:101], v[200:201], off offset:2064
	global_load_dwordx2 v[102:103], v[200:201], off offset:2080
	global_load_dwordx2 v[104:105], v[200:201], off offset:2096
	global_load_dwordx2 v[106:107], v[200:201], off offset:2112
	global_load_dwordx2 v[108:109], v[200:201], off offset:2128
	global_load_dwordx2 v[110:111], v[200:201], off offset:2144
	global_load_dwordx2 v[112:113], v[200:201], off offset:2160
	global_load_dwordx2 v[162:163], v[200:201], off offset:-1024
	global_load_dwordx2 v[164:165], v[200:201], off offset:-1008
	global_load_dwordx2 v[166:167], v[200:201], off offset:-992
	global_load_dwordx2 v[168:169], v[200:201], off offset:-976
	global_load_dwordx2 v[170:171], v[200:201], off offset:-960
	global_load_dwordx2 v[172:173], v[200:201], off offset:-944
	global_load_dwordx2 v[174:175], v[200:201], off offset:-928
	global_load_dwordx2 v[176:177], v[200:201], off offset:-912
	global_load_dwordx2 v[178:179], v[196:197], off offset:1024
	global_load_dwordx2 v[180:181], v[196:197], off offset:1040
	global_load_dwordx2 v[182:183], v[196:197], off offset:1056
	global_load_dwordx2 v[184:185], v[196:197], off offset:1072
	global_load_dwordx2 v[186:187], v[196:197], off offset:1088
	global_load_dwordx2 v[188:189], v[196:197], off offset:1104
	global_load_dwordx2 v[190:191], v[196:197], off offset:1120
	global_load_dwordx2 v[192:193], v[196:197], off offset:1136
	ds_read_b128 v[204:207], v116 offset:0
	ds_read_b128 v[208:211], v116 offset:512
	ds_read_b128 v[212:215], v116 offset:1024
	ds_read_b128 v[216:219], v116 offset:1536
	ds_read_b128 v[220:223], v116 offset:2048
	ds_read_b128 v[226:229], v116 offset:32
	ds_read_b128 v[230:233], v116 offset:544
	ds_read_b128 v[234:237], v116 offset:1056
	ds_read_b128 v[238:241], v116 offset:1568
	ds_read_b128 v[242:245], v116 offset:2080
	v_cmp_gt_i32_e32 vcc, s87, v118
	v_mov_b32_e32 v0, 0xff
	v_mov_b32_e32 v119, 0xfff
	v_cndmask_b32_e32 v0, v0, v119, vcc
	v_and_b32_e32 v119, v118, v0
	v_cmp_ne_u32_e64 s[38:39], 0, v119
	v_cmp_ne_u32_e64 s[40:41], v119, v0
	s_waitcnt vmcnt(26)
	v_cvt_f32_f16_e32 v130, v66
	v_cvt_f32_f16_sdwa v131, v66 dst_sel:DWORD dst_unused:UNUSED_PAD src0_sel:WORD_1
	v_cvt_f32_f16_e32 v246, v82
	v_cvt_f32_f16_sdwa v247, v82 dst_sel:DWORD dst_unused:UNUSED_PAD src0_sel:WORD_1
	v_add_f32_e32 v130, v130, v246
	v_add_f32_e32 v131, v131, v247
	v_cvt_f32_f16_e32 v132, v67
	v_cvt_f32_f16_sdwa v133, v67 dst_sel:DWORD dst_unused:UNUSED_PAD src0_sel:WORD_1
	v_cvt_f32_f16_e32 v246, v83
	v_cvt_f32_f16_sdwa v247, v83 dst_sel:DWORD dst_unused:UNUSED_PAD src0_sel:WORD_1
	v_add_f32_e32 v132, v132, v246
	v_add_f32_e32 v133, v133, v247
	v_cvt_f32_f16_e32 v134, v68
	v_cvt_f32_f16_sdwa v135, v68 dst_sel:DWORD dst_unused:UNUSED_PAD src0_sel:WORD_1
	v_cvt_f32_f16_e32 v246, v84
	v_cvt_f32_f16_sdwa v247, v84 dst_sel:DWORD dst_unused:UNUSED_PAD src0_sel:WORD_1
	v_add_f32_e32 v134, v134, v246
	v_add_f32_e32 v135, v135, v247
	v_cvt_f32_f16_e32 v136, v69
	v_cvt_f32_f16_sdwa v137, v69 dst_sel:DWORD dst_unused:UNUSED_PAD src0_sel:WORD_1
	v_cvt_f32_f16_e32 v246, v85
	v_cvt_f32_f16_sdwa v247, v85 dst_sel:DWORD dst_unused:UNUSED_PAD src0_sel:WORD_1
	v_add_f32_e32 v136, v136, v246
	v_add_f32_e32 v137, v137, v247
	v_cvt_f32_f16_e32 v138, v70
	v_cvt_f32_f16_sdwa v139, v70 dst_sel:DWORD dst_unused:UNUSED_PAD src0_sel:WORD_1
	v_cvt_f32_f16_e32 v246, v86
	v_cvt_f32_f16_sdwa v247, v86 dst_sel:DWORD dst_unused:UNUSED_PAD src0_sel:WORD_1
	v_add_f32_e32 v138, v138, v246
	v_add_f32_e32 v139, v139, v247
	v_cvt_f32_f16_e32 v140, v71
	v_cvt_f32_f16_sdwa v141, v71 dst_sel:DWORD dst_unused:UNUSED_PAD src0_sel:WORD_1
	v_cvt_f32_f16_e32 v246, v87
	v_cvt_f32_f16_sdwa v247, v87 dst_sel:DWORD dst_unused:UNUSED_PAD src0_sel:WORD_1
	v_add_f32_e32 v140, v140, v246
	v_add_f32_e32 v141, v141, v247
	v_cvt_f32_f16_e32 v142, v72
	v_cvt_f32_f16_sdwa v143, v72 dst_sel:DWORD dst_unused:UNUSED_PAD src0_sel:WORD_1
	v_cvt_f32_f16_e32 v246, v88
	v_cvt_f32_f16_sdwa v247, v88 dst_sel:DWORD dst_unused:UNUSED_PAD src0_sel:WORD_1
	v_add_f32_e32 v142, v142, v246
	v_add_f32_e32 v143, v143, v247
	v_cvt_f32_f16_e32 v144, v73
	v_cvt_f32_f16_sdwa v145, v73 dst_sel:DWORD dst_unused:UNUSED_PAD src0_sel:WORD_1
	v_cvt_f32_f16_e32 v246, v89
	v_cvt_f32_f16_sdwa v247, v89 dst_sel:DWORD dst_unused:UNUSED_PAD src0_sel:WORD_1
	v_add_f32_e32 v144, v144, v246
	v_add_f32_e32 v145, v145, v247
	v_cvt_f32_f16_e32 v146, v74
	v_cvt_f32_f16_sdwa v147, v74 dst_sel:DWORD dst_unused:UNUSED_PAD src0_sel:WORD_1
	v_cvt_f32_f16_e32 v246, v90
	v_cvt_f32_f16_sdwa v247, v90 dst_sel:DWORD dst_unused:UNUSED_PAD src0_sel:WORD_1
	v_add_f32_e32 v146, v146, v246
	v_add_f32_e32 v147, v147, v247
	v_cvt_f32_f16_e32 v148, v75
	v_cvt_f32_f16_sdwa v149, v75 dst_sel:DWORD dst_unused:UNUSED_PAD src0_sel:WORD_1
	v_cvt_f32_f16_e32 v246, v91
	v_cvt_f32_f16_sdwa v247, v91 dst_sel:DWORD dst_unused:UNUSED_PAD src0_sel:WORD_1
	v_add_f32_e32 v148, v148, v246
	v_add_f32_e32 v149, v149, v247
	v_cvt_f32_f16_e32 v150, v76
	v_cvt_f32_f16_sdwa v151, v76 dst_sel:DWORD dst_unused:UNUSED_PAD src0_sel:WORD_1
	v_cvt_f32_f16_e32 v246, v92
; DI void phase_post(const P& p, int l, char* smem) {
;     ...
;           y[mi][4 * g + 0] = (float)f.x + (float)bk.x; y[mi][4 * g + 1] = (float)f.y + (float)bk.y;
;           y[mi][4 * g + 2] = (float)f.z + (float)bk.z; y[mi][4 * g + 3] = (float)f.w + (float)bk.w;
;           sum += y[mi][4 * g] + y[mi][4 * g + 1] + y[mi][4 * g + 2] + y[mi][4 * g + 3];
;         }
;       sum += shx(sum, 32);
;       const float mean = sum * (1.f / 64.f);
;       float vs = 0.f;
; #pragma unroll
;       for (int mi = 0; mi < 2; ++mi)
; #pragma unroll
;         for (int i = 0; i < 16; ++i) { const float dlt = y[mi][i] - mean; vs += dlt * dlt; }
;       vs += shx(vs, 32);
;       const float rstd = rsqrtf(vs * (1.f / 64.f) + 64e-5f);
	v_cvt_f32_f16_sdwa v247, v92 dst_sel:DWORD dst_unused:UNUSED_PAD src0_sel:WORD_1
	v_add_f32_e32 v150, v150, v246
	v_add_f32_e32 v151, v151, v247
	v_cvt_f32_f16_e32 v152, v77
	v_cvt_f32_f16_sdwa v153, v77 dst_sel:DWORD dst_unused:UNUSED_PAD src0_sel:WORD_1
	v_cvt_f32_f16_e32 v246, v93
	v_cvt_f32_f16_sdwa v247, v93 dst_sel:DWORD dst_unused:UNUSED_PAD src0_sel:WORD_1
	v_add_f32_e32 v152, v152, v246
	v_add_f32_e32 v153, v153, v247
	v_cvt_f32_f16_e32 v154, v78
	v_cvt_f32_f16_sdwa v155, v78 dst_sel:DWORD dst_unused:UNUSED_PAD src0_sel:WORD_1
	v_cvt_f32_f16_e32 v246, v94
	v_cvt_f32_f16_sdwa v247, v94 dst_sel:DWORD dst_unused:UNUSED_PAD src0_sel:WORD_1
	v_add_f32_e32 v154, v154, v246
	v_add_f32_e32 v155, v155, v247
	v_cvt_f32_f16_e32 v156, v79
	v_cvt_f32_f16_sdwa v157, v79 dst_sel:DWORD dst_unused:UNUSED_PAD src0_sel:WORD_1
	v_cvt_f32_f16_e32 v246, v95
	v_cvt_f32_f16_sdwa v247, v95 dst_sel:DWORD dst_unused:UNUSED_PAD src0_sel:WORD_1
	v_add_f32_e32 v156, v156, v246
	v_add_f32_e32 v157, v157, v247
	v_cvt_f32_f16_e32 v158, v80
	v_cvt_f32_f16_sdwa v159, v80 dst_sel:DWORD dst_unused:UNUSED_PAD src0_sel:WORD_1
	v_cvt_f32_f16_e32 v246, v96
	v_cvt_f32_f16_sdwa v247, v96 dst_sel:DWORD dst_unused:UNUSED_PAD src0_sel:WORD_1
	v_add_f32_e32 v158, v158, v246
	v_add_f32_e32 v159, v159, v247
	v_cvt_f32_f16_e32 v160, v81
	v_cvt_f32_f16_sdwa v161, v81 dst_sel:DWORD dst_unused:UNUSED_PAD src0_sel:WORD_1
	v_cvt_f32_f16_e32 v246, v97
	v_cvt_f32_f16_sdwa v247, v97 dst_sel:DWORD dst_unused:UNUSED_PAD src0_sel:WORD_1
	v_add_f32_e32 v160, v160, v246
	v_add_f32_e32 v161, v161, v247
	v_add_f32_e32 v246, v130, v131
	v_add_f32_e32 v246, v246, v132
	v_add_f32_e32 v246, v246, v133
	v_add_f32_e32 v246, v246, v134
	v_add_f32_e32 v246, v246, v135
	v_add_f32_e32 v246, v246, v136
	v_add_f32_e32 v246, v246, v137
	v_add_f32_e32 v247, v138, v139
	v_add_f32_e32 v247, v247, v140
	v_add_f32_e32 v247, v247, v141
	v_add_f32_e32 v247, v247, v142
	v_add_f32_e32 v247, v247, v143
	v_add_f32_e32 v247, v247, v144
	v_add_f32_e32 v247, v247, v145
	v_add_f32_e32 v248, v146, v147
	v_add_f32_e32 v248, v248, v148
	v_add_f32_e32 v248, v248, v149
	v_add_f32_e32 v248, v248, v150
	v_add_f32_e32 v248, v248, v151
	v_add_f32_e32 v248, v248, v152
	v_add_f32_e32 v248, v248, v153
	v_add_f32_e32 v249, v154, v155
	v_add_f32_e32 v249, v249, v156
	v_add_f32_e32 v249, v249, v157
	v_add_f32_e32 v249, v249, v158
	v_add_f32_e32 v249, v249, v159
	v_add_f32_e32 v249, v249, v160
	v_add_f32_e32 v249, v249, v161
	v_add_f32_e32 v246, v246, v247
	v_add_f32_e32 v248, v248, v249
	v_add_f32_e32 v246, v246, v248
	v_mov_b32_e32 v247, v246
	s_nop 1
	v_permlane32_swap_b32_e32 v246, v247
	v_add_f32_e32 v246, v246, v247
	v_mul_f32_e32 v246, 0x3c800000, v246
	v_sub_f32_e32 v130, v130, v246
	v_sub_f32_e32 v131, v131, v246
	v_sub_f32_e32 v132, v132, v246
	v_sub_f32_e32 v133, v133, v246
	v_sub_f32_e32 v134, v134, v246
	v_sub_f32_e32 v135, v135, v246
	v_sub_f32_e32 v136, v136, v246
	v_sub_f32_e32 v137, v137, v246
	v_sub_f32_e32 v138, v138, v246
	v_sub_f32_e32 v139, v139, v246
	v_sub_f32_e32 v140, v140, v246
	v_sub_f32_e32 v141, v141, v246
	v_sub_f32_e32 v142, v142, v246
	v_sub_f32_e32 v143, v143, v246
	v_sub_f32_e32 v144, v144, v246
	v_sub_f32_e32 v145, v145, v246
	v_sub_f32_e32 v146, v146, v246
	v_sub_f32_e32 v147, v147, v246
	v_sub_f32_e32 v148, v148, v246
	v_sub_f32_e32 v149, v149, v246
	v_sub_f32_e32 v150, v150, v246
	v_sub_f32_e32 v151, v151, v246
	v_sub_f32_e32 v152, v152, v246
	v_sub_f32_e32 v153, v153, v246
	v_sub_f32_e32 v154, v154, v246
	v_sub_f32_e32 v155, v155, v246
	v_sub_f32_e32 v156, v156, v246
	v_sub_f32_e32 v157, v157, v246
	v_sub_f32_e32 v158, v158, v246
	v_sub_f32_e32 v159, v159, v246
	v_sub_f32_e32 v160, v160, v246
	v_sub_f32_e32 v161, v161, v246
	v_mul_f32_e32 v247, v130, v130
	v_fmac_f32_e32 v247, v131, v131
	v_fmac_f32_e32 v247, v132, v132
	v_fmac_f32_e32 v247, v133, v133
	v_fmac_f32_e32 v247, v134, v134
	v_fmac_f32_e32 v247, v135, v135
	v_fmac_f32_e32 v247, v136, v136
	v_fmac_f32_e32 v247, v137, v137
	v_mul_f32_e32 v248, v138, v138
	v_fmac_f32_e32 v248, v139, v139
	v_fmac_f32_e32 v248, v140, v140
	v_fmac_f32_e32 v248, v141, v141
	v_fmac_f32_e32 v248, v142, v142
	v_fmac_f32_e32 v248, v143, v143
	v_fmac_f32_e32 v248, v144, v144
	v_fmac_f32_e32 v248, v145, v145
	v_mul_f32_e32 v249, v146, v146
	v_fmac_f32_e32 v249, v147, v147
	v_fmac_f32_e32 v249, v148, v148
	v_fmac_f32_e32 v249, v149, v149
	v_fmac_f32_e32 v249, v150, v150
	v_fmac_f32_e32 v249, v151, v151
	v_fmac_f32_e32 v249, v152, v152
	v_fmac_f32_e32 v249, v153, v153
	v_mul_f32_e32 v250, v154, v154
	v_fmac_f32_e32 v250, v155, v155
	v_fmac_f32_e32 v250, v156, v156
	v_fmac_f32_e32 v250, v157, v157
	v_fmac_f32_e32 v250, v158, v158
	v_fmac_f32_e32 v250, v159, v159
	v_fmac_f32_e32 v250, v160, v160
	v_fmac_f32_e32 v250, v161, v161
	v_add_f32_e32 v247, v247, v248
	v_add_f32_e32 v249, v249, v250
	v_add_f32_e32 v247, v247, v249
	v_mov_b32_e32 v248, v247
	s_nop 1
	v_permlane32_swap_b32_e32 v247, v248
	v_add_f32_e32 v247, v247, v248
	v_mov_b32_e32 v248, 0x3a27c5ac
	v_fmamk_f32 v247, v247, 0x3c800000, v248
	v_rsq_f32_e32 v247, v247
	s_nop 0
	v_mul_f32_e32 v130, v130, v247
	v_mul_f32_e32 v131, v131, v247
	v_mul_f32_e32 v132, v132, v247
	v_mul_f32_e32 v133, v133, v247
	v_mul_f32_e32 v134, v134, v247
	v_mul_f32_e32 v135, v135, v247
	v_mul_f32_e32 v136, v136, v247
	v_mul_f32_e32 v137, v137, v247
	v_mul_f32_e32 v138, v138, v247
	v_mul_f32_e32 v139, v139, v247
	v_mul_f32_e32 v140, v140, v247
	v_mul_f32_e32 v141, v141, v247
	v_mul_f32_e32 v142, v142, v247
	v_mul_f32_e32 v143, v143, v247
	v_mul_f32_e32 v144, v144, v247
	v_mul_f32_e32 v145, v145, v247
	v_mul_f32_e32 v146, v146, v247
	v_mul_f32_e32 v147, v147, v247
	v_mul_f32_e32 v148, v148, v247
	v_mul_f32_e32 v149, v149, v247
	v_mul_f32_e32 v150, v150, v247
	v_mul_f32_e32 v151, v151, v247
	v_mul_f32_e32 v152, v152, v247
	v_mul_f32_e32 v153, v153, v247
	v_mul_f32_e32 v154, v154, v247
	v_mul_f32_e32 v155, v155, v247
	v_mul_f32_e32 v156, v156, v247
	v_mul_f32_e32 v157, v157, v247
	v_mul_f32_e32 v158, v158, v247
	v_mul_f32_e32 v159, v159, v247
	v_mul_f32_e32 v160, v160, v247
	v_mul_f32_e32 v161, v161, v247
	s_waitcnt vmcnt(24)
; #define L(ph, l, hf) hipLaunchKernelGGL(k_phase<ph>, dim3(G), dim3(256), 0, stream, p, l, hf)
; DI void phase_post(const P& p, int l, char* smem) {
;     ...
;       const float bsum = bs[(size_t)row * 8 + head] + bs[((size_t)TA + row) * 8 + head];
; #pragma unroll
;       for (int mi = 0; mi < 2; ++mi)
; #pragma unroll
;         for (int g = 0; g < 4; ++g) {
;           const int cb_ = m0 + wm * 64 + mi * 32 + 8 * g + 4 * hh;
;           const h16* vp = rkv + (size_t)row * 1536 + 1024 + cb_;
;           h16x4 v1 = *(const h16x4*)vp, v0, v2;
;           v0.x = v0.y = v0.z = v0.w = (h16)0.f; v2 = v0;
;           if (pos > 0) v0 = *(const h16x4*)(vp - 1536);
;           if (pos < L - 1) v2 = *(const h16x4*)(vp + 1536);
;           h16x4 o;
; #pragma unroll
;           for (int e = 0; e < 4; ++e) {
;             const int cc = cb_ + e;
;             const float vv = cvp[cc] * (float)v0[e] + cvp[1536 + cc] * (float)v1[e] + cvp[3072 + cc] * (float)v2[e];
;             const float val = ((y[mi][4 * g + e] - mean) * rstd * lng[cc] + lnb[cc] + bsum * vv) * acc[mi][ni][4 * g + e];
;             o[e] = (h16)val;
;           }
;           *(h16x4*)(rkv + (size_t)row * 1536 + cb_) = o;
;         }
	v_add_f32_e32 v194, v194, v195
	s_waitcnt vmcnt(0)
	s_waitcnt lgkmcnt(5)
	v_cvt_f32_f16_e32 v66, v98
	v_cvt_f32_f16_sdwa v67, v98 dst_sel:DWORD dst_unused:UNUSED_PAD src0_sel:WORD_1
	v_cvt_f32_f16_e32 v70, v162
	v_cvt_f32_f16_sdwa v71, v162 dst_sel:DWORD dst_unused:UNUSED_PAD src0_sel:WORD_1
	v_cvt_f32_f16_e32 v74, v178
	v_cvt_f32_f16_sdwa v75, v178 dst_sel:DWORD dst_unused:UNUSED_PAD src0_sel:WORD_1
	v_cvt_f32_f16_e32 v68, v99
	v_cvt_f32_f16_sdwa v69, v99 dst_sel:DWORD dst_unused:UNUSED_PAD src0_sel:WORD_1
	v_cvt_f32_f16_e32 v72, v163
	v_cvt_f32_f16_sdwa v73, v163 dst_sel:DWORD dst_unused:UNUSED_PAD src0_sel:WORD_1
	v_cvt_f32_f16_e32 v76, v179
	v_cvt_f32_f16_sdwa v77, v179 dst_sel:DWORD dst_unused:UNUSED_PAD src0_sel:WORD_1
	v_cndmask_b32_e64 v70, 0, v70, s[38:39]
	v_cndmask_b32_e64 v74, 0, v74, s[40:41]
	v_cndmask_b32_e64 v71, 0, v71, s[38:39]
	v_cndmask_b32_e64 v75, 0, v75, s[40:41]
	v_cndmask_b32_e64 v72, 0, v72, s[38:39]
	v_cndmask_b32_e64 v76, 0, v76, s[40:41]
	v_cndmask_b32_e64 v73, 0, v73, s[38:39]
	v_cndmask_b32_e64 v77, 0, v77, s[40:41]
	v_mul_f32_e32 v66, v208, v66
	v_fmac_f32_e32 v66, v204, v70
	v_fmac_f32_e32 v66, v212, v74
	v_mul_f32_e32 v67, v209, v67
	v_fmac_f32_e32 v67, v205, v71
	v_fmac_f32_e32 v67, v213, v75
	v_mul_f32_e32 v68, v210, v68
	v_fmac_f32_e32 v68, v206, v72
	v_fmac_f32_e32 v68, v214, v76
	v_mul_f32_e32 v69, v211, v69
	v_fmac_f32_e32 v69, v207, v73
	v_fmac_f32_e32 v69, v215, v77
	v_fma_f32 v70, v130, v216, v220
	v_fmac_f32_e32 v70, v194, v66
	v_mul_f32_e32 v70, v50, v70
	v_fma_f32 v71, v131, v217, v221
	v_fmac_f32_e32 v71, v194, v67
	v_mul_f32_e32 v71, v51, v71
	v_fma_f32 v72, v132, v218, v222
	v_fmac_f32_e32 v72, v194, v68
	v_mul_f32_e32 v72, v52, v72
	v_fma_f32 v73, v133, v219, v223
	v_fmac_f32_e32 v73, v194, v69
	v_mul_f32_e32 v73, v53, v73
	v_cvt_pk_f16_f32 v78, v70, v71
	v_cvt_pk_f16_f32 v79, v72, v73
	global_store_dwordx2 v[200:201], v[78:79], off
	ds_read_b128 v[204:207], v116 offset:64
	ds_read_b128 v[208:211], v116 offset:576
	ds_read_b128 v[212:215], v116 offset:1088
	ds_read_b128 v[216:219], v116 offset:1600
	ds_read_b128 v[220:223], v116 offset:2112
	s_nop 0
	s_waitcnt lgkmcnt(5)
	v_cvt_f32_f16_e32 v66, v100
	v_cvt_f32_f16_sdwa v67, v100 dst_sel:DWORD dst_unused:UNUSED_PAD src0_sel:WORD_1
	v_cvt_f32_f16_e32 v70, v164
	v_cvt_f32_f16_sdwa v71, v164 dst_sel:DWORD dst_unused:UNUSED_PAD src0_sel:WORD_1
	v_cvt_f32_f16_e32 v74, v180
	v_cvt_f32_f16_sdwa v75, v180 dst_sel:DWORD dst_unused:UNUSED_PAD src0_sel:WORD_1
	v_cvt_f32_f16_e32 v68, v101
	v_cvt_f32_f16_sdwa v69, v101 dst_sel:DWORD dst_unused:UNUSED_PAD src0_sel:WORD_1
	v_cvt_f32_f16_e32 v72, v165
	v_cvt_f32_f16_sdwa v73, v165 dst_sel:DWORD dst_unused:UNUSED_PAD src0_sel:WORD_1
	v_cvt_f32_f16_e32 v76, v181
	v_cvt_f32_f16_sdwa v77, v181 dst_sel:DWORD dst_unused:UNUSED_PAD src0_sel:WORD_1
	v_cndmask_b32_e64 v70, 0, v70, s[38:39]
	v_cndmask_b32_e64 v74, 0, v74, s[40:41]
	v_cndmask_b32_e64 v71, 0, v71, s[38:39]
	v_cndmask_b32_e64 v75, 0, v75, s[40:41]
	v_cndmask_b32_e64 v72, 0, v72, s[38:39]
	v_cndmask_b32_e64 v76, 0, v76, s[40:41]
	v_cndmask_b32_e64 v73, 0, v73, s[38:39]
	v_cndmask_b32_e64 v77, 0, v77, s[40:41]
	v_mul_f32_e32 v66, v230, v66
	v_fmac_f32_e32 v66, v226, v70
	v_fmac_f32_e32 v66, v234, v74
	v_mul_f32_e32 v67, v231, v67
	v_fmac_f32_e32 v67, v227, v71
	v_fmac_f32_e32 v67, v235, v75
	v_mul_f32_e32 v68, v232, v68
	v_fmac_f32_e32 v68, v228, v72
	v_fmac_f32_e32 v68, v236, v76
	v_mul_f32_e32 v69, v233, v69
	v_fmac_f32_e32 v69, v229, v73
	v_fmac_f32_e32 v69, v237, v77
	v_fma_f32 v70, v134, v238, v242
	v_fmac_f32_e32 v70, v194, v66
	v_mul_f32_e32 v70, v54, v70
	v_fma_f32 v71, v135, v239, v243
	v_fmac_f32_e32 v71, v194, v67
	v_mul_f32_e32 v71, v55, v71
	v_fma_f32 v72, v136, v240, v244
	v_fmac_f32_e32 v72, v194, v68
	v_mul_f32_e32 v72, v56, v72
	v_fma_f32 v73, v137, v241, v245
	v_fmac_f32_e32 v73, v194, v69
	v_mul_f32_e32 v73, v57, v73
	v_cvt_pk_f16_f32 v78, v70, v71
	v_cvt_pk_f16_f32 v79, v72, v73
	global_store_dwordx2 v[200:201], v[78:79], off offset:16
	ds_read_b128 v[226:229], v116 offset:96
	ds_read_b128 v[230:233], v116 offset:608
	ds_read_b128 v[234:237], v116 offset:1120
	ds_read_b128 v[238:241], v116 offset:1632
	ds_read_b128 v[242:245], v116 offset:2144
	s_nop 0
	s_waitcnt lgkmcnt(5)
	v_cvt_f32_f16_e32 v66, v102
	v_cvt_f32_f16_sdwa v67, v102 dst_sel:DWORD dst_unused:UNUSED_PAD src0_sel:WORD_1
	v_cvt_f32_f16_e32 v70, v166
	v_cvt_f32_f16_sdwa v71, v166 dst_sel:DWORD dst_unused:UNUSED_PAD src0_sel:WORD_1
	v_cvt_f32_f16_e32 v74, v182
	v_cvt_f32_f16_sdwa v75, v182 dst_sel:DWORD dst_unused:UNUSED_PAD src0_sel:WORD_1
	v_cvt_f32_f16_e32 v68, v103
	v_cvt_f32_f16_sdwa v69, v103 dst_sel:DWORD dst_unused:UNUSED_PAD src0_sel:WORD_1
	v_cvt_f32_f16_e32 v72, v167
	v_cvt_f32_f16_sdwa v73, v167 dst_sel:DWORD dst_unused:UNUSED_PAD src0_sel:WORD_1
	v_cvt_f32_f16_e32 v76, v183
	v_cvt_f32_f16_sdwa v77, v183 dst_sel:DWORD dst_unused:UNUSED_PAD src0_sel:WORD_1
	v_cndmask_b32_e64 v70, 0, v70, s[38:39]
	v_cndmask_b32_e64 v74, 0, v74, s[40:41]
	v_cndmask_b32_e64 v71, 0, v71, s[38:39]
	v_cndmask_b32_e64 v75, 0, v75, s[40:41]
	v_cndmask_b32_e64 v72, 0, v72, s[38:39]
	v_cndmask_b32_e64 v76, 0, v76, s[40:41]
	v_cndmask_b32_e64 v73, 0, v73, s[38:39]
	v_cndmask_b32_e64 v77, 0, v77, s[40:41]
	v_mul_f32_e32 v66, v208, v66
	v_fmac_f32_e32 v66, v204, v70
	v_fmac_f32_e32 v66, v212, v74
	v_mul_f32_e32 v67, v209, v67
	v_fmac_f32_e32 v67, v205, v71
	v_fmac_f32_e32 v67, v213, v75
	v_mul_f32_e32 v68, v210, v68
	v_fmac_f32_e32 v68, v206, v72
	v_fmac_f32_e32 v68, v214, v76
	v_mul_f32_e32 v69, v211, v69
	v_fmac_f32_e32 v69, v207, v73
	v_fmac_f32_e32 v69, v215, v77
	v_fma_f32 v70, v138, v216, v220
	v_fmac_f32_e32 v70, v194, v66
	v_mul_f32_e32 v70, v58, v70
	v_fma_f32 v71, v139, v217, v221
	v_fmac_f32_e32 v71, v194, v67
	v_mul_f32_e32 v71, v59, v71
	v_fma_f32 v72, v140, v218, v222
	v_fmac_f32_e32 v72, v194, v68
	v_mul_f32_e32 v72, v60, v72
	v_fma_f32 v73, v141, v219, v223
	v_fmac_f32_e32 v73, v194, v69
	v_mul_f32_e32 v73, v61, v73
	v_cvt_pk_f16_f32 v78, v70, v71
	v_cvt_pk_f16_f32 v79, v72, v73
	global_store_dwordx2 v[200:201], v[78:79], off offset:32
	ds_read_b128 v[204:207], v116 offset:128
	ds_read_b128 v[208:211], v116 offset:640
	ds_read_b128 v[212:215], v116 offset:1152
	ds_read_b128 v[216:219], v116 offset:1664
	ds_read_b128 v[220:223], v116 offset:2176
	s_nop 0
	s_waitcnt lgkmcnt(5)
; #define L(ph, l, hf) hipLaunchKernelGGL(k_phase<ph>, dim3(G), dim3(256), 0, stream, p, l, hf)
; DI void phase_post(const P& p, int l, char* smem) {
;     ...
; #pragma unroll
;       for (int mi = 0; mi < 2; ++mi)
; #pragma unroll
;         for (int g = 0; g < 4; ++g) {
;           const int cb_ = m0 + wm * 64 + mi * 32 + 8 * g + 4 * hh;
;           const h16* vp = rkv + (size_t)row * 1536 + 1024 + cb_;
;           h16x4 v1 = *(const h16x4*)vp, v0, v2;
;           v0.x = v0.y = v0.z = v0.w = (h16)0.f; v2 = v0;
;           if (pos > 0) v0 = *(const h16x4*)(vp - 1536);
;           if (pos < L - 1) v2 = *(const h16x4*)(vp + 1536);
;           h16x4 o;
; #pragma unroll
;           for (int e = 0; e < 4; ++e) {
;             const int cc = cb_ + e;
;             const float vv = cvp[cc] * (float)v0[e] + cvp[1536 + cc] * (float)v1[e] + cvp[3072 + cc] * (float)v2[e];
;             const float val = ((y[mi][4 * g + e] - mean) * rstd * lng[cc] + lnb[cc] + bsum * vv) * acc[mi][ni][4 * g + e];
;             o[e] = (h16)val;
;           }
;           *(h16x4*)(rkv + (size_t)row * 1536 + cb_) = o;
;         }
	v_cvt_f32_f16_e32 v66, v104
	v_cvt_f32_f16_sdwa v67, v104 dst_sel:DWORD dst_unused:UNUSED_PAD src0_sel:WORD_1
	v_cvt_f32_f16_e32 v70, v168
	v_cvt_f32_f16_sdwa v71, v168 dst_sel:DWORD dst_unused:UNUSED_PAD src0_sel:WORD_1
	v_cvt_f32_f16_e32 v74, v184
	v_cvt_f32_f16_sdwa v75, v184 dst_sel:DWORD dst_unused:UNUSED_PAD src0_sel:WORD_1
	v_cvt_f32_f16_e32 v68, v105
	v_cvt_f32_f16_sdwa v69, v105 dst_sel:DWORD dst_unused:UNUSED_PAD src0_sel:WORD_1
	v_cvt_f32_f16_e32 v72, v169
	v_cvt_f32_f16_sdwa v73, v169 dst_sel:DWORD dst_unused:UNUSED_PAD src0_sel:WORD_1
	v_cvt_f32_f16_e32 v76, v185
	v_cvt_f32_f16_sdwa v77, v185 dst_sel:DWORD dst_unused:UNUSED_PAD src0_sel:WORD_1
	v_cndmask_b32_e64 v70, 0, v70, s[38:39]
	v_cndmask_b32_e64 v74, 0, v74, s[40:41]
	v_cndmask_b32_e64 v71, 0, v71, s[38:39]
	v_cndmask_b32_e64 v75, 0, v75, s[40:41]
	v_cndmask_b32_e64 v72, 0, v72, s[38:39]
	v_cndmask_b32_e64 v76, 0, v76, s[40:41]
	v_cndmask_b32_e64 v73, 0, v73, s[38:39]
	v_cndmask_b32_e64 v77, 0, v77, s[40:41]
	v_mul_f32_e32 v66, v230, v66
	v_fmac_f32_e32 v66, v226, v70
	v_fmac_f32_e32 v66, v234, v74
	v_mul_f32_e32 v67, v231, v67
	v_fmac_f32_e32 v67, v227, v71
	v_fmac_f32_e32 v67, v235, v75
	v_mul_f32_e32 v68, v232, v68
	v_fmac_f32_e32 v68, v228, v72
	v_fmac_f32_e32 v68, v236, v76
	v_mul_f32_e32 v69, v233, v69
	v_fmac_f32_e32 v69, v229, v73
	v_fmac_f32_e32 v69, v237, v77
	v_fma_f32 v70, v142, v238, v242
	v_fmac_f32_e32 v70, v194, v66
	v_mul_f32_e32 v70, v62, v70
	v_fma_f32 v71, v143, v239, v243
	v_fmac_f32_e32 v71, v194, v67
	v_mul_f32_e32 v71, v63, v71
	v_fma_f32 v72, v144, v240, v244
	v_fmac_f32_e32 v72, v194, v68
	v_mul_f32_e32 v72, v64, v72
	v_fma_f32 v73, v145, v241, v245
	v_fmac_f32_e32 v73, v194, v69
	v_mul_f32_e32 v73, v65, v73
	v_cvt_pk_f16_f32 v78, v70, v71
	v_cvt_pk_f16_f32 v79, v72, v73
	global_store_dwordx2 v[200:201], v[78:79], off offset:48
	ds_read_b128 v[226:229], v116 offset:160
	ds_read_b128 v[230:233], v116 offset:672
	ds_read_b128 v[234:237], v116 offset:1184
	ds_read_b128 v[238:241], v116 offset:1696
	ds_read_b128 v[242:245], v116 offset:2208
	s_nop 0
	s_waitcnt lgkmcnt(5)
	v_cvt_f32_f16_e32 v66, v106
	v_cvt_f32_f16_sdwa v67, v106 dst_sel:DWORD dst_unused:UNUSED_PAD src0_sel:WORD_1
	v_cvt_f32_f16_e32 v70, v170
	v_cvt_f32_f16_sdwa v71, v170 dst_sel:DWORD dst_unused:UNUSED_PAD src0_sel:WORD_1
	v_cvt_f32_f16_e32 v74, v186
	v_cvt_f32_f16_sdwa v75, v186 dst_sel:DWORD dst_unused:UNUSED_PAD src0_sel:WORD_1
	v_cvt_f32_f16_e32 v68, v107
	v_cvt_f32_f16_sdwa v69, v107 dst_sel:DWORD dst_unused:UNUSED_PAD src0_sel:WORD_1
	v_cvt_f32_f16_e32 v72, v171
	v_cvt_f32_f16_sdwa v73, v171 dst_sel:DWORD dst_unused:UNUSED_PAD src0_sel:WORD_1
	v_cvt_f32_f16_e32 v76, v187
	v_cvt_f32_f16_sdwa v77, v187 dst_sel:DWORD dst_unused:UNUSED_PAD src0_sel:WORD_1
	v_cndmask_b32_e64 v70, 0, v70, s[38:39]
	v_cndmask_b32_e64 v74, 0, v74, s[40:41]
	v_cndmask_b32_e64 v71, 0, v71, s[38:39]
	v_cndmask_b32_e64 v75, 0, v75, s[40:41]
	v_cndmask_b32_e64 v72, 0, v72, s[38:39]
	v_cndmask_b32_e64 v76, 0, v76, s[40:41]
	v_cndmask_b32_e64 v73, 0, v73, s[38:39]
	v_cndmask_b32_e64 v77, 0, v77, s[40:41]
	v_mul_f32_e32 v66, v208, v66
	v_fmac_f32_e32 v66, v204, v70
	v_fmac_f32_e32 v66, v212, v74
	v_mul_f32_e32 v67, v209, v67
	v_fmac_f32_e32 v67, v205, v71
	v_fmac_f32_e32 v67, v213, v75
	v_mul_f32_e32 v68, v210, v68
	v_fmac_f32_e32 v68, v206, v72
	v_fmac_f32_e32 v68, v214, v76
	v_mul_f32_e32 v69, v211, v69
	v_fmac_f32_e32 v69, v207, v73
	v_fmac_f32_e32 v69, v215, v77
	v_fma_f32 v70, v146, v216, v220
	v_fmac_f32_e32 v70, v194, v66
	v_mul_f32_e32 v70, v34, v70
	v_fma_f32 v71, v147, v217, v221
	v_fmac_f32_e32 v71, v194, v67
	v_mul_f32_e32 v71, v35, v71
	v_fma_f32 v72, v148, v218, v222
	v_fmac_f32_e32 v72, v194, v68
	v_mul_f32_e32 v72, v36, v72
	v_fma_f32 v73, v149, v219, v223
	v_fmac_f32_e32 v73, v194, v69
	v_mul_f32_e32 v73, v37, v73
	v_cvt_pk_f16_f32 v78, v70, v71
	v_cvt_pk_f16_f32 v79, v72, v73
	global_store_dwordx2 v[200:201], v[78:79], off offset:64
	ds_read_b128 v[204:207], v116 offset:192
	ds_read_b128 v[208:211], v116 offset:704
	ds_read_b128 v[212:215], v116 offset:1216
	ds_read_b128 v[216:219], v116 offset:1728
	ds_read_b128 v[220:223], v116 offset:2240
	s_nop 0
	s_waitcnt lgkmcnt(5)
	v_cvt_f32_f16_e32 v66, v108
	v_cvt_f32_f16_sdwa v67, v108 dst_sel:DWORD dst_unused:UNUSED_PAD src0_sel:WORD_1
	v_cvt_f32_f16_e32 v70, v172
	v_cvt_f32_f16_sdwa v71, v172 dst_sel:DWORD dst_unused:UNUSED_PAD src0_sel:WORD_1
	v_cvt_f32_f16_e32 v74, v188
	v_cvt_f32_f16_sdwa v75, v188 dst_sel:DWORD dst_unused:UNUSED_PAD src0_sel:WORD_1
	v_cvt_f32_f16_e32 v68, v109
	v_cvt_f32_f16_sdwa v69, v109 dst_sel:DWORD dst_unused:UNUSED_PAD src0_sel:WORD_1
	v_cvt_f32_f16_e32 v72, v173
	v_cvt_f32_f16_sdwa v73, v173 dst_sel:DWORD dst_unused:UNUSED_PAD src0_sel:WORD_1
	v_cvt_f32_f16_e32 v76, v189
	v_cvt_f32_f16_sdwa v77, v189 dst_sel:DWORD dst_unused:UNUSED_PAD src0_sel:WORD_1
	v_cndmask_b32_e64 v70, 0, v70, s[38:39]
	v_cndmask_b32_e64 v74, 0, v74, s[40:41]
	v_cndmask_b32_e64 v71, 0, v71, s[38:39]
	v_cndmask_b32_e64 v75, 0, v75, s[40:41]
	v_cndmask_b32_e64 v72, 0, v72, s[38:39]
	v_cndmask_b32_e64 v76, 0, v76, s[40:41]
	v_cndmask_b32_e64 v73, 0, v73, s[38:39]
	v_cndmask_b32_e64 v77, 0, v77, s[40:41]
	v_mul_f32_e32 v66, v230, v66
	v_fmac_f32_e32 v66, v226, v70
	v_fmac_f32_e32 v66, v234, v74
	v_mul_f32_e32 v67, v231, v67
	v_fmac_f32_e32 v67, v227, v71
	v_fmac_f32_e32 v67, v235, v75
	v_mul_f32_e32 v68, v232, v68
	v_fmac_f32_e32 v68, v228, v72
	v_fmac_f32_e32 v68, v236, v76
	v_mul_f32_e32 v69, v233, v69
	v_fmac_f32_e32 v69, v229, v73
	v_fmac_f32_e32 v69, v237, v77
	v_fma_f32 v70, v150, v238, v242
	v_fmac_f32_e32 v70, v194, v66
	v_mul_f32_e32 v70, v38, v70
	v_fma_f32 v71, v151, v239, v243
	v_fmac_f32_e32 v71, v194, v67
	v_mul_f32_e32 v71, v39, v71
	v_fma_f32 v72, v152, v240, v244
	v_fmac_f32_e32 v72, v194, v68
	v_mul_f32_e32 v72, v40, v72
	v_fma_f32 v73, v153, v241, v245
	v_fmac_f32_e32 v73, v194, v69
	v_mul_f32_e32 v73, v41, v73
	v_cvt_pk_f16_f32 v78, v70, v71
	v_cvt_pk_f16_f32 v79, v72, v73
	global_store_dwordx2 v[200:201], v[78:79], off offset:80
	ds_read_b128 v[226:229], v116 offset:224
	ds_read_b128 v[230:233], v116 offset:736
	ds_read_b128 v[234:237], v116 offset:1248
	ds_read_b128 v[238:241], v116 offset:1760
	ds_read_b128 v[242:245], v116 offset:2272
	s_nop 0
	s_waitcnt lgkmcnt(5)
; #define L(ph, l, hf) hipLaunchKernelGGL(k_phase<ph>, dim3(G), dim3(256), 0, stream, p, l, hf)
; DI void phase_post(const P& p, int l, char* smem) {
;     ...
;     for (int ni = 0; ni < 2; ++ni) {
;       const int row = n0 + wn * 64 + ni * 32 + (lane & 31);
;       const bool lat = row < TL;
;       const int pos = lat ? (row & 4095) : ((row - TL) & 255);
;       const int L = lat ? 4096 : 256;
;       float y[2][16];
;       float sum = 0.f;
; #pragma unroll
;       for (int mi = 0; mi < 2; ++mi)
; #pragma unroll
;         for (int g = 0; g < 4; ++g) {
;           const int cb_ = m0 + wm * 64 + mi * 32 + 8 * g + 4 * hh;
;           h16x4 f = *(const h16x4*)(sof + (size_t)row * 512 + cb_), bk = *(const h16x4*)(sob + (size_t)row * 512 + cb_);
;           y[mi][4 * g + 0] = (float)f.x + (float)bk.x; y[mi][4 * g + 1] = (float)f.y + (float)bk.y;
;           y[mi][4 * g + 2] = (float)f.z + (float)bk.z; y[mi][4 * g + 3] = (float)f.w + (float)bk.w;
;     ...
;       for (int mi = 0; mi < 2; ++mi)
; #pragma unroll
;         for (int g = 0; g < 4; ++g) {
;           const int cb_ = m0 + wm * 64 + mi * 32 + 8 * g + 4 * hh;
;           const h16* vp = rkv + (size_t)row * 1536 + 1024 + cb_;
;           h16x4 v1 = *(const h16x4*)vp, v0, v2;
;           v0.x = v0.y = v0.z = v0.w = (h16)0.f; v2 = v0;
;           if (pos > 0) v0 = *(const h16x4*)(vp - 1536);
;           if (pos < L - 1) v2 = *(const h16x4*)(vp + 1536);
;           h16x4 o;
; #pragma unroll
;           for (int e = 0; e < 4; ++e) {
;             const int cc = cb_ + e;
;             const float vv = cvp[cc] * (float)v0[e] + cvp[1536 + cc] * (float)v1[e] + cvp[3072 + cc] * (float)v2[e];
;             const float val = ((y[mi][4 * g + e] - mean) * rstd * lng[cc] + lnb[cc] + bsum * vv) * acc[mi][ni][4 * g + e];
;             o[e] = (h16)val;
;           }
;           *(h16x4*)(rkv + (size_t)row * 1536 + cb_) = o;
;         }
	v_cvt_f32_f16_e32 v66, v110
	v_cvt_f32_f16_sdwa v67, v110 dst_sel:DWORD dst_unused:UNUSED_PAD src0_sel:WORD_1
	v_cvt_f32_f16_e32 v70, v174
	v_cvt_f32_f16_sdwa v71, v174 dst_sel:DWORD dst_unused:UNUSED_PAD src0_sel:WORD_1
	v_cvt_f32_f16_e32 v74, v190
	v_cvt_f32_f16_sdwa v75, v190 dst_sel:DWORD dst_unused:UNUSED_PAD src0_sel:WORD_1
	v_cvt_f32_f16_e32 v68, v111
	v_cvt_f32_f16_sdwa v69, v111 dst_sel:DWORD dst_unused:UNUSED_PAD src0_sel:WORD_1
	v_cvt_f32_f16_e32 v72, v175
	v_cvt_f32_f16_sdwa v73, v175 dst_sel:DWORD dst_unused:UNUSED_PAD src0_sel:WORD_1
	v_cvt_f32_f16_e32 v76, v191
	v_cvt_f32_f16_sdwa v77, v191 dst_sel:DWORD dst_unused:UNUSED_PAD src0_sel:WORD_1
	v_cndmask_b32_e64 v70, 0, v70, s[38:39]
	v_cndmask_b32_e64 v74, 0, v74, s[40:41]
	v_cndmask_b32_e64 v71, 0, v71, s[38:39]
	v_cndmask_b32_e64 v75, 0, v75, s[40:41]
	v_cndmask_b32_e64 v72, 0, v72, s[38:39]
	v_cndmask_b32_e64 v76, 0, v76, s[40:41]
	v_cndmask_b32_e64 v73, 0, v73, s[38:39]
	v_cndmask_b32_e64 v77, 0, v77, s[40:41]
	v_mul_f32_e32 v66, v208, v66
	v_fmac_f32_e32 v66, v204, v70
	v_fmac_f32_e32 v66, v212, v74
	v_mul_f32_e32 v67, v209, v67
	v_fmac_f32_e32 v67, v205, v71
	v_fmac_f32_e32 v67, v213, v75
	v_mul_f32_e32 v68, v210, v68
	v_fmac_f32_e32 v68, v206, v72
	v_fmac_f32_e32 v68, v214, v76
	v_mul_f32_e32 v69, v211, v69
	v_fmac_f32_e32 v69, v207, v73
	v_fmac_f32_e32 v69, v215, v77
	v_fma_f32 v70, v154, v216, v220
	v_fmac_f32_e32 v70, v194, v66
	v_mul_f32_e32 v70, v42, v70
	v_fma_f32 v71, v155, v217, v221
	v_fmac_f32_e32 v71, v194, v67
	v_mul_f32_e32 v71, v43, v71
	v_fma_f32 v72, v156, v218, v222
	v_fmac_f32_e32 v72, v194, v68
	v_mul_f32_e32 v72, v44, v72
	v_fma_f32 v73, v157, v219, v223
	v_fmac_f32_e32 v73, v194, v69
	v_mul_f32_e32 v73, v45, v73
	v_cvt_pk_f16_f32 v78, v70, v71
	v_cvt_pk_f16_f32 v79, v72, v73
	global_store_dwordx2 v[200:201], v[78:79], off offset:96
	s_nop 0
	s_waitcnt lgkmcnt(0)
	v_cvt_f32_f16_e32 v66, v112
	v_cvt_f32_f16_sdwa v67, v112 dst_sel:DWORD dst_unused:UNUSED_PAD src0_sel:WORD_1
	v_cvt_f32_f16_e32 v70, v176
	v_cvt_f32_f16_sdwa v71, v176 dst_sel:DWORD dst_unused:UNUSED_PAD src0_sel:WORD_1
	v_cvt_f32_f16_e32 v74, v192
	v_cvt_f32_f16_sdwa v75, v192 dst_sel:DWORD dst_unused:UNUSED_PAD src0_sel:WORD_1
	v_cvt_f32_f16_e32 v68, v113
	v_cvt_f32_f16_sdwa v69, v113 dst_sel:DWORD dst_unused:UNUSED_PAD src0_sel:WORD_1
	v_cvt_f32_f16_e32 v72, v177
	v_cvt_f32_f16_sdwa v73, v177 dst_sel:DWORD dst_unused:UNUSED_PAD src0_sel:WORD_1
	v_cvt_f32_f16_e32 v76, v193
	v_cvt_f32_f16_sdwa v77, v193 dst_sel:DWORD dst_unused:UNUSED_PAD src0_sel:WORD_1
	v_cndmask_b32_e64 v70, 0, v70, s[38:39]
	v_cndmask_b32_e64 v74, 0, v74, s[40:41]
	v_cndmask_b32_e64 v71, 0, v71, s[38:39]
	v_cndmask_b32_e64 v75, 0, v75, s[40:41]
	v_cndmask_b32_e64 v72, 0, v72, s[38:39]
	v_cndmask_b32_e64 v76, 0, v76, s[40:41]
	v_cndmask_b32_e64 v73, 0, v73, s[38:39]
	v_cndmask_b32_e64 v77, 0, v77, s[40:41]
	v_mul_f32_e32 v66, v230, v66
	v_fmac_f32_e32 v66, v226, v70
	v_fmac_f32_e32 v66, v234, v74
	v_mul_f32_e32 v67, v231, v67
	v_fmac_f32_e32 v67, v227, v71
	v_fmac_f32_e32 v67, v235, v75
	v_mul_f32_e32 v68, v232, v68
	v_fmac_f32_e32 v68, v228, v72
	v_fmac_f32_e32 v68, v236, v76
	v_mul_f32_e32 v69, v233, v69
	v_fmac_f32_e32 v69, v229, v73
	v_fmac_f32_e32 v69, v237, v77
	v_fma_f32 v70, v158, v238, v242
	v_fmac_f32_e32 v70, v194, v66
	v_mul_f32_e32 v70, v46, v70
	v_fma_f32 v71, v159, v239, v243
	v_fmac_f32_e32 v71, v194, v67
	v_mul_f32_e32 v71, v47, v71
	v_fma_f32 v72, v160, v240, v244
	v_fmac_f32_e32 v72, v194, v68
	v_mul_f32_e32 v72, v48, v72
	v_fma_f32 v73, v161, v241, v245
	v_fmac_f32_e32 v73, v194, v69
	v_mul_f32_e32 v73, v49, v73
	v_cvt_pk_f16_f32 v78, v70, v71
	v_cvt_pk_f16_f32 v79, v72, v73
	global_store_dwordx2 v[200:201], v[78:79], off offset:112
	v_add_u32_e32 v118, 32, v114
	v_mov_b32_e32 v119, 0
	v_lshlrev_b64 v[246:247], 10, v[118:119]
	v_lshlrev_b32_e32 v0, 1, v115
	v_add_co_u32_e32 v246, vcc, v246, v0
	s_nop 1
	v_addc_co_u32_e32 v247, vcc, 0, v247, vcc
	v_lshl_add_u64 v[248:249], s[8:9], 0, v[246:247]
	v_lshl_add_u64 v[246:247], s[6:7], 0, v[246:247]
	s_movk_i32 s20, 0xc00
	v_mad_u64_u32 v[200:201], s[2:3], v118, s20, v[0:1]
	v_lshl_add_u64 v[200:201], s[4:5], 0, v[200:201]
	s_mov_b64 s[2:3], 0x1000
	v_lshl_add_u64 v[196:197], v[200:201], 0, s[2:3]
	v_lshl_add_u32 v198, v118, 3, v117
	v_mov_b32_e32 v199, 0
	v_lshlrev_b64 v[198:199], 2, v[198:199]
	v_lshl_add_u64 v[198:199], s[10:11], 0, v[198:199]
	global_load_dwordx2 v[66:67], v[246:247], off
	global_load_dwordx2 v[68:69], v[246:247], off offset:16
	global_load_dwordx2 v[70:71], v[246:247], off offset:32
	global_load_dwordx2 v[72:73], v[246:247], off offset:48
	global_load_dwordx2 v[74:75], v[246:247], off offset:64
	global_load_dwordx2 v[76:77], v[246:247], off offset:80
	global_load_dwordx2 v[78:79], v[246:247], off offset:96
	global_load_dwordx2 v[80:81], v[246:247], off offset:112
	global_load_dwordx2 v[82:83], v[248:249], off
	global_load_dwordx2 v[84:85], v[248:249], off offset:16
	global_load_dwordx2 v[86:87], v[248:249], off offset:32
	global_load_dwordx2 v[88:89], v[248:249], off offset:48
	global_load_dwordx2 v[90:91], v[248:249], off offset:64
	global_load_dwordx2 v[92:93], v[248:249], off offset:80
	global_load_dwordx2 v[94:95], v[248:249], off offset:96
	global_load_dwordx2 v[96:97], v[248:249], off offset:112
	global_load_dword v194, v[198:199], off
	v_add_co_u32_e32 v198, vcc, 0x110000, v198
	s_nop 1
	v_addc_co_u32_e32 v199, vcc, 0, v199, vcc
	global_load_dword v195, v[198:199], off
	global_load_dwordx2 v[98:99], v[200:201], off offset:2048
	global_load_dwordx2 v[100:101], v[200:201], off offset:2064
	global_load_dwordx2 v[102:103], v[200:201], off offset:2080
; #define L(ph, l, hf) hipLaunchKernelGGL(k_phase<ph>, dim3(G), dim3(256), 0, stream, p, l, hf)
; DI void phase_post(const P& p, int l, char* smem) {
;     ...
;       const int row = n0 + wn * 64 + ni * 32 + (lane & 31);
;       const bool lat = row < TL;
;       const int pos = lat ? (row & 4095) : ((row - TL) & 255);
;       const int L = lat ? 4096 : 256;
;       float y[2][16];
;       float sum = 0.f;
; #pragma unroll
;       for (int mi = 0; mi < 2; ++mi)
; #pragma unroll
;         for (int g = 0; g < 4; ++g) {
;           const int cb_ = m0 + wm * 64 + mi * 32 + 8 * g + 4 * hh;
;           h16x4 f = *(const h16x4*)(sof + (size_t)row * 512 + cb_), bk = *(const h16x4*)(sob + (size_t)row * 512 + cb_);
;           y[mi][4 * g + 0] = (float)f.x + (float)bk.x; y[mi][4 * g + 1] = (float)f.y + (float)bk.y;
;           y[mi][4 * g + 2] = (float)f.z + (float)bk.z; y[mi][4 * g + 3] = (float)f.w + (float)bk.w;
;           sum += y[mi][4 * g] + y[mi][4 * g + 1] + y[mi][4 * g + 2] + y[mi][4 * g + 3];
;         }
;       sum += shx(sum, 32);
;       const float mean = sum * (1.f / 64.f);
;       float vs = 0.f;
; #pragma unroll
;       for (int mi = 0; mi < 2; ++mi)
; #pragma unroll
;         for (int i = 0; i < 16; ++i) { const float dlt = y[mi][i] - mean; vs += dlt * dlt; }
;       vs += shx(vs, 32);
;       const float rstd = rsqrtf(vs * (1.f / 64.f) + 64e-5f);
;       const float bsum = bs[(size_t)row * 8 + head] + bs[((size_t)TA + row) * 8 + head];
; #pragma unroll
;       for (int mi = 0; mi < 2; ++mi)
; #pragma unroll
;         for (int g = 0; g < 4; ++g) {
;           const int cb_ = m0 + wm * 64 + mi * 32 + 8 * g + 4 * hh;
;           const h16* vp = rkv + (size_t)row * 1536 + 1024 + cb_;
;           h16x4 v1 = *(const h16x4*)vp, v0, v2;
;           v0.x = v0.y = v0.z = v0.w = (h16)0.f; v2 = v0;
;           if (pos > 0) v0 = *(const h16x4*)(vp - 1536);
;           if (pos < L - 1) v2 = *(const h16x4*)(vp + 1536);
	global_load_dwordx2 v[104:105], v[200:201], off offset:2096
	global_load_dwordx2 v[106:107], v[200:201], off offset:2112
	global_load_dwordx2 v[108:109], v[200:201], off offset:2128
	global_load_dwordx2 v[110:111], v[200:201], off offset:2144
	global_load_dwordx2 v[112:113], v[200:201], off offset:2160
	global_load_dwordx2 v[162:163], v[200:201], off offset:-1024
	global_load_dwordx2 v[164:165], v[200:201], off offset:-1008
	global_load_dwordx2 v[166:167], v[200:201], off offset:-992
	global_load_dwordx2 v[168:169], v[200:201], off offset:-976
	global_load_dwordx2 v[170:171], v[200:201], off offset:-960
	global_load_dwordx2 v[172:173], v[200:201], off offset:-944
	global_load_dwordx2 v[174:175], v[200:201], off offset:-928
	global_load_dwordx2 v[176:177], v[200:201], off offset:-912
	global_load_dwordx2 v[178:179], v[196:197], off offset:1024
	global_load_dwordx2 v[180:181], v[196:197], off offset:1040
	global_load_dwordx2 v[182:183], v[196:197], off offset:1056
	global_load_dwordx2 v[184:185], v[196:197], off offset:1072
	global_load_dwordx2 v[186:187], v[196:197], off offset:1088
	global_load_dwordx2 v[188:189], v[196:197], off offset:1104
	global_load_dwordx2 v[190:191], v[196:197], off offset:1120
	global_load_dwordx2 v[192:193], v[196:197], off offset:1136
	ds_read_b128 v[204:207], v116 offset:0
	ds_read_b128 v[208:211], v116 offset:512
	ds_read_b128 v[212:215], v116 offset:1024
	ds_read_b128 v[216:219], v116 offset:1536
	ds_read_b128 v[220:223], v116 offset:2048
	ds_read_b128 v[226:229], v116 offset:32
	ds_read_b128 v[230:233], v116 offset:544
	ds_read_b128 v[234:237], v116 offset:1056
	ds_read_b128 v[238:241], v116 offset:1568
	ds_read_b128 v[242:245], v116 offset:2080
	v_cmp_gt_i32_e32 vcc, s87, v118
	v_mov_b32_e32 v0, 0xff
	v_mov_b32_e32 v119, 0xfff
	v_cndmask_b32_e32 v0, v0, v119, vcc
	v_and_b32_e32 v119, v118, v0
	v_cmp_ne_u32_e64 s[38:39], 0, v119
	v_cmp_ne_u32_e64 s[40:41], v119, v0
	s_waitcnt vmcnt(26)
	v_cvt_f32_f16_e32 v130, v66
	v_cvt_f32_f16_sdwa v131, v66 dst_sel:DWORD dst_unused:UNUSED_PAD src0_sel:WORD_1
	v_cvt_f32_f16_e32 v246, v82
	v_cvt_f32_f16_sdwa v247, v82 dst_sel:DWORD dst_unused:UNUSED_PAD src0_sel:WORD_1
	v_add_f32_e32 v130, v130, v246
	v_add_f32_e32 v131, v131, v247
	v_cvt_f32_f16_e32 v132, v67
	v_cvt_f32_f16_sdwa v133, v67 dst_sel:DWORD dst_unused:UNUSED_PAD src0_sel:WORD_1
	v_cvt_f32_f16_e32 v246, v83
	v_cvt_f32_f16_sdwa v247, v83 dst_sel:DWORD dst_unused:UNUSED_PAD src0_sel:WORD_1
	v_add_f32_e32 v132, v132, v246
	v_add_f32_e32 v133, v133, v247
	v_cvt_f32_f16_e32 v134, v68
	v_cvt_f32_f16_sdwa v135, v68 dst_sel:DWORD dst_unused:UNUSED_PAD src0_sel:WORD_1
	v_cvt_f32_f16_e32 v246, v84
	v_cvt_f32_f16_sdwa v247, v84 dst_sel:DWORD dst_unused:UNUSED_PAD src0_sel:WORD_1
	v_add_f32_e32 v134, v134, v246
	v_add_f32_e32 v135, v135, v247
	v_cvt_f32_f16_e32 v136, v69
	v_cvt_f32_f16_sdwa v137, v69 dst_sel:DWORD dst_unused:UNUSED_PAD src0_sel:WORD_1
	v_cvt_f32_f16_e32 v246, v85
	v_cvt_f32_f16_sdwa v247, v85 dst_sel:DWORD dst_unused:UNUSED_PAD src0_sel:WORD_1
	v_add_f32_e32 v136, v136, v246
	v_add_f32_e32 v137, v137, v247
	v_cvt_f32_f16_e32 v138, v70
	v_cvt_f32_f16_sdwa v139, v70 dst_sel:DWORD dst_unused:UNUSED_PAD src0_sel:WORD_1
	v_cvt_f32_f16_e32 v246, v86
	v_cvt_f32_f16_sdwa v247, v86 dst_sel:DWORD dst_unused:UNUSED_PAD src0_sel:WORD_1
	v_add_f32_e32 v138, v138, v246
	v_add_f32_e32 v139, v139, v247
	v_cvt_f32_f16_e32 v140, v71
	v_cvt_f32_f16_sdwa v141, v71 dst_sel:DWORD dst_unused:UNUSED_PAD src0_sel:WORD_1
	v_cvt_f32_f16_e32 v246, v87
	v_cvt_f32_f16_sdwa v247, v87 dst_sel:DWORD dst_unused:UNUSED_PAD src0_sel:WORD_1
	v_add_f32_e32 v140, v140, v246
	v_add_f32_e32 v141, v141, v247
	v_cvt_f32_f16_e32 v142, v72
	v_cvt_f32_f16_sdwa v143, v72 dst_sel:DWORD dst_unused:UNUSED_PAD src0_sel:WORD_1
	v_cvt_f32_f16_e32 v246, v88
	v_cvt_f32_f16_sdwa v247, v88 dst_sel:DWORD dst_unused:UNUSED_PAD src0_sel:WORD_1
	v_add_f32_e32 v142, v142, v246
	v_add_f32_e32 v143, v143, v247
	v_cvt_f32_f16_e32 v144, v73
	v_cvt_f32_f16_sdwa v145, v73 dst_sel:DWORD dst_unused:UNUSED_PAD src0_sel:WORD_1
	v_cvt_f32_f16_e32 v246, v89
	v_cvt_f32_f16_sdwa v247, v89 dst_sel:DWORD dst_unused:UNUSED_PAD src0_sel:WORD_1
	v_add_f32_e32 v144, v144, v246
	v_add_f32_e32 v145, v145, v247
	v_cvt_f32_f16_e32 v146, v74
	v_cvt_f32_f16_sdwa v147, v74 dst_sel:DWORD dst_unused:UNUSED_PAD src0_sel:WORD_1
	v_cvt_f32_f16_e32 v246, v90
	v_cvt_f32_f16_sdwa v247, v90 dst_sel:DWORD dst_unused:UNUSED_PAD src0_sel:WORD_1
	v_add_f32_e32 v146, v146, v246
	v_add_f32_e32 v147, v147, v247
	v_cvt_f32_f16_e32 v148, v75
	v_cvt_f32_f16_sdwa v149, v75 dst_sel:DWORD dst_unused:UNUSED_PAD src0_sel:WORD_1
	v_cvt_f32_f16_e32 v246, v91
	v_cvt_f32_f16_sdwa v247, v91 dst_sel:DWORD dst_unused:UNUSED_PAD src0_sel:WORD_1
	v_add_f32_e32 v148, v148, v246
	v_add_f32_e32 v149, v149, v247
	v_cvt_f32_f16_e32 v150, v76
	v_cvt_f32_f16_sdwa v151, v76 dst_sel:DWORD dst_unused:UNUSED_PAD src0_sel:WORD_1
	v_cvt_f32_f16_e32 v246, v92
	v_cvt_f32_f16_sdwa v247, v92 dst_sel:DWORD dst_unused:UNUSED_PAD src0_sel:WORD_1
	v_add_f32_e32 v150, v150, v246
	v_add_f32_e32 v151, v151, v247
	v_cvt_f32_f16_e32 v152, v77
	v_cvt_f32_f16_sdwa v153, v77 dst_sel:DWORD dst_unused:UNUSED_PAD src0_sel:WORD_1
	v_cvt_f32_f16_e32 v246, v93
	v_cvt_f32_f16_sdwa v247, v93 dst_sel:DWORD dst_unused:UNUSED_PAD src0_sel:WORD_1
	v_add_f32_e32 v152, v152, v246
	v_add_f32_e32 v153, v153, v247
	v_cvt_f32_f16_e32 v154, v78
	v_cvt_f32_f16_sdwa v155, v78 dst_sel:DWORD dst_unused:UNUSED_PAD src0_sel:WORD_1
	v_cvt_f32_f16_e32 v246, v94
	v_cvt_f32_f16_sdwa v247, v94 dst_sel:DWORD dst_unused:UNUSED_PAD src0_sel:WORD_1
	v_add_f32_e32 v154, v154, v246
; DI void phase_post(const P& p, int l, char* smem) {
;     ...
;           y[mi][4 * g + 0] = (float)f.x + (float)bk.x; y[mi][4 * g + 1] = (float)f.y + (float)bk.y;
;           y[mi][4 * g + 2] = (float)f.z + (float)bk.z; y[mi][4 * g + 3] = (float)f.w + (float)bk.w;
;           sum += y[mi][4 * g] + y[mi][4 * g + 1] + y[mi][4 * g + 2] + y[mi][4 * g + 3];
;         }
;       sum += shx(sum, 32);
;       const float mean = sum * (1.f / 64.f);
;       float vs = 0.f;
; #pragma unroll
;       for (int mi = 0; mi < 2; ++mi)
; #pragma unroll
;         for (int i = 0; i < 16; ++i) { const float dlt = y[mi][i] - mean; vs += dlt * dlt; }
;       vs += shx(vs, 32);
;       const float rstd = rsqrtf(vs * (1.f / 64.f) + 64e-5f);
;       const float bsum = bs[(size_t)row * 8 + head] + bs[((size_t)TA + row) * 8 + head];
	v_add_f32_e32 v155, v155, v247
	v_cvt_f32_f16_e32 v156, v79
	v_cvt_f32_f16_sdwa v157, v79 dst_sel:DWORD dst_unused:UNUSED_PAD src0_sel:WORD_1
	v_cvt_f32_f16_e32 v246, v95
	v_cvt_f32_f16_sdwa v247, v95 dst_sel:DWORD dst_unused:UNUSED_PAD src0_sel:WORD_1
	v_add_f32_e32 v156, v156, v246
	v_add_f32_e32 v157, v157, v247
	v_cvt_f32_f16_e32 v158, v80
	v_cvt_f32_f16_sdwa v159, v80 dst_sel:DWORD dst_unused:UNUSED_PAD src0_sel:WORD_1
	v_cvt_f32_f16_e32 v246, v96
	v_cvt_f32_f16_sdwa v247, v96 dst_sel:DWORD dst_unused:UNUSED_PAD src0_sel:WORD_1
	v_add_f32_e32 v158, v158, v246
	v_add_f32_e32 v159, v159, v247
	v_cvt_f32_f16_e32 v160, v81
	v_cvt_f32_f16_sdwa v161, v81 dst_sel:DWORD dst_unused:UNUSED_PAD src0_sel:WORD_1
	v_cvt_f32_f16_e32 v246, v97
	v_cvt_f32_f16_sdwa v247, v97 dst_sel:DWORD dst_unused:UNUSED_PAD src0_sel:WORD_1
	v_add_f32_e32 v160, v160, v246
	v_add_f32_e32 v161, v161, v247
	v_add_f32_e32 v246, v130, v131
	v_add_f32_e32 v246, v246, v132
	v_add_f32_e32 v246, v246, v133
	v_add_f32_e32 v246, v246, v134
	v_add_f32_e32 v246, v246, v135
	v_add_f32_e32 v246, v246, v136
	v_add_f32_e32 v246, v246, v137
	v_add_f32_e32 v247, v138, v139
	v_add_f32_e32 v247, v247, v140
	v_add_f32_e32 v247, v247, v141
	v_add_f32_e32 v247, v247, v142
	v_add_f32_e32 v247, v247, v143
	v_add_f32_e32 v247, v247, v144
	v_add_f32_e32 v247, v247, v145
	v_add_f32_e32 v248, v146, v147
	v_add_f32_e32 v248, v248, v148
	v_add_f32_e32 v248, v248, v149
	v_add_f32_e32 v248, v248, v150
	v_add_f32_e32 v248, v248, v151
	v_add_f32_e32 v248, v248, v152
	v_add_f32_e32 v248, v248, v153
	v_add_f32_e32 v249, v154, v155
	v_add_f32_e32 v249, v249, v156
	v_add_f32_e32 v249, v249, v157
	v_add_f32_e32 v249, v249, v158
	v_add_f32_e32 v249, v249, v159
	v_add_f32_e32 v249, v249, v160
	v_add_f32_e32 v249, v249, v161
	v_add_f32_e32 v246, v246, v247
	v_add_f32_e32 v248, v248, v249
	v_add_f32_e32 v246, v246, v248
	v_mov_b32_e32 v247, v246
	s_nop 1
	v_permlane32_swap_b32_e32 v246, v247
	v_add_f32_e32 v246, v246, v247
	v_mul_f32_e32 v246, 0x3c800000, v246
	v_sub_f32_e32 v130, v130, v246
	v_sub_f32_e32 v131, v131, v246
	v_sub_f32_e32 v132, v132, v246
	v_sub_f32_e32 v133, v133, v246
	v_sub_f32_e32 v134, v134, v246
	v_sub_f32_e32 v135, v135, v246
	v_sub_f32_e32 v136, v136, v246
	v_sub_f32_e32 v137, v137, v246
	v_sub_f32_e32 v138, v138, v246
	v_sub_f32_e32 v139, v139, v246
	v_sub_f32_e32 v140, v140, v246
	v_sub_f32_e32 v141, v141, v246
	v_sub_f32_e32 v142, v142, v246
	v_sub_f32_e32 v143, v143, v246
	v_sub_f32_e32 v144, v144, v246
	v_sub_f32_e32 v145, v145, v246
	v_sub_f32_e32 v146, v146, v246
	v_sub_f32_e32 v147, v147, v246
	v_sub_f32_e32 v148, v148, v246
	v_sub_f32_e32 v149, v149, v246
	v_sub_f32_e32 v150, v150, v246
	v_sub_f32_e32 v151, v151, v246
	v_sub_f32_e32 v152, v152, v246
	v_sub_f32_e32 v153, v153, v246
	v_sub_f32_e32 v154, v154, v246
	v_sub_f32_e32 v155, v155, v246
	v_sub_f32_e32 v156, v156, v246
	v_sub_f32_e32 v157, v157, v246
	v_sub_f32_e32 v158, v158, v246
	v_sub_f32_e32 v159, v159, v246
	v_sub_f32_e32 v160, v160, v246
	v_sub_f32_e32 v161, v161, v246
	v_mul_f32_e32 v247, v130, v130
	v_fmac_f32_e32 v247, v131, v131
	v_fmac_f32_e32 v247, v132, v132
	v_fmac_f32_e32 v247, v133, v133
	v_fmac_f32_e32 v247, v134, v134
	v_fmac_f32_e32 v247, v135, v135
	v_fmac_f32_e32 v247, v136, v136
	v_fmac_f32_e32 v247, v137, v137
	v_mul_f32_e32 v248, v138, v138
	v_fmac_f32_e32 v248, v139, v139
	v_fmac_f32_e32 v248, v140, v140
	v_fmac_f32_e32 v248, v141, v141
	v_fmac_f32_e32 v248, v142, v142
	v_fmac_f32_e32 v248, v143, v143
	v_fmac_f32_e32 v248, v144, v144
	v_fmac_f32_e32 v248, v145, v145
	v_mul_f32_e32 v249, v146, v146
	v_fmac_f32_e32 v249, v147, v147
	v_fmac_f32_e32 v249, v148, v148
	v_fmac_f32_e32 v249, v149, v149
	v_fmac_f32_e32 v249, v150, v150
	v_fmac_f32_e32 v249, v151, v151
	v_fmac_f32_e32 v249, v152, v152
	v_fmac_f32_e32 v249, v153, v153
	v_mul_f32_e32 v250, v154, v154
	v_fmac_f32_e32 v250, v155, v155
	v_fmac_f32_e32 v250, v156, v156
	v_fmac_f32_e32 v250, v157, v157
	v_fmac_f32_e32 v250, v158, v158
	v_fmac_f32_e32 v250, v159, v159
	v_fmac_f32_e32 v250, v160, v160
	v_fmac_f32_e32 v250, v161, v161
	v_add_f32_e32 v247, v247, v248
	v_add_f32_e32 v249, v249, v250
	v_add_f32_e32 v247, v247, v249
	v_mov_b32_e32 v248, v247
	s_nop 1
	v_permlane32_swap_b32_e32 v247, v248
	v_add_f32_e32 v247, v247, v248
	v_mov_b32_e32 v248, 0x3a27c5ac
	v_fmamk_f32 v247, v247, 0x3c800000, v248
	v_rsq_f32_e32 v247, v247
	s_nop 0
	v_mul_f32_e32 v130, v130, v247
	v_mul_f32_e32 v131, v131, v247
	v_mul_f32_e32 v132, v132, v247
	v_mul_f32_e32 v133, v133, v247
	v_mul_f32_e32 v134, v134, v247
	v_mul_f32_e32 v135, v135, v247
	v_mul_f32_e32 v136, v136, v247
	v_mul_f32_e32 v137, v137, v247
	v_mul_f32_e32 v138, v138, v247
	v_mul_f32_e32 v139, v139, v247
	v_mul_f32_e32 v140, v140, v247
	v_mul_f32_e32 v141, v141, v247
	v_mul_f32_e32 v142, v142, v247
	v_mul_f32_e32 v143, v143, v247
	v_mul_f32_e32 v144, v144, v247
	v_mul_f32_e32 v145, v145, v247
	v_mul_f32_e32 v146, v146, v247
	v_mul_f32_e32 v147, v147, v247
	v_mul_f32_e32 v148, v148, v247
	v_mul_f32_e32 v149, v149, v247
	v_mul_f32_e32 v150, v150, v247
	v_mul_f32_e32 v151, v151, v247
	v_mul_f32_e32 v152, v152, v247
	v_mul_f32_e32 v153, v153, v247
	v_mul_f32_e32 v154, v154, v247
	v_mul_f32_e32 v155, v155, v247
	v_mul_f32_e32 v156, v156, v247
	v_mul_f32_e32 v157, v157, v247
	v_mul_f32_e32 v158, v158, v247
	v_mul_f32_e32 v159, v159, v247
	v_mul_f32_e32 v160, v160, v247
	v_mul_f32_e32 v161, v161, v247
	s_waitcnt vmcnt(24)
	v_add_f32_e32 v194, v194, v195
	s_waitcnt vmcnt(0)
	s_waitcnt lgkmcnt(5)
; #define L(ph, l, hf) hipLaunchKernelGGL(k_phase<ph>, dim3(G), dim3(256), 0, stream, p, l, hf)
; DI void phase_post(const P& p, int l, char* smem) {
;     ...
; #pragma unroll
;       for (int mi = 0; mi < 2; ++mi)
; #pragma unroll
;         for (int g = 0; g < 4; ++g) {
;           const int cb_ = m0 + wm * 64 + mi * 32 + 8 * g + 4 * hh;
;           const h16* vp = rkv + (size_t)row * 1536 + 1024 + cb_;
;           h16x4 v1 = *(const h16x4*)vp, v0, v2;
;           v0.x = v0.y = v0.z = v0.w = (h16)0.f; v2 = v0;
;           if (pos > 0) v0 = *(const h16x4*)(vp - 1536);
;           if (pos < L - 1) v2 = *(const h16x4*)(vp + 1536);
;           h16x4 o;
; #pragma unroll
;           for (int e = 0; e < 4; ++e) {
;             const int cc = cb_ + e;
;             const float vv = cvp[cc] * (float)v0[e] + cvp[1536 + cc] * (float)v1[e] + cvp[3072 + cc] * (float)v2[e];
;             const float val = ((y[mi][4 * g + e] - mean) * rstd * lng[cc] + lnb[cc] + bsum * vv) * acc[mi][ni][4 * g + e];
;             o[e] = (h16)val;
;           }
;           *(h16x4*)(rkv + (size_t)row * 1536 + cb_) = o;
;         }
	v_cvt_f32_f16_e32 v66, v98
	v_cvt_f32_f16_sdwa v67, v98 dst_sel:DWORD dst_unused:UNUSED_PAD src0_sel:WORD_1
	v_cvt_f32_f16_e32 v70, v162
	v_cvt_f32_f16_sdwa v71, v162 dst_sel:DWORD dst_unused:UNUSED_PAD src0_sel:WORD_1
	v_cvt_f32_f16_e32 v74, v178
	v_cvt_f32_f16_sdwa v75, v178 dst_sel:DWORD dst_unused:UNUSED_PAD src0_sel:WORD_1
	v_cvt_f32_f16_e32 v68, v99
	v_cvt_f32_f16_sdwa v69, v99 dst_sel:DWORD dst_unused:UNUSED_PAD src0_sel:WORD_1
	v_cvt_f32_f16_e32 v72, v163
	v_cvt_f32_f16_sdwa v73, v163 dst_sel:DWORD dst_unused:UNUSED_PAD src0_sel:WORD_1
	v_cvt_f32_f16_e32 v76, v179
	v_cvt_f32_f16_sdwa v77, v179 dst_sel:DWORD dst_unused:UNUSED_PAD src0_sel:WORD_1
	v_cndmask_b32_e64 v70, 0, v70, s[38:39]
	v_cndmask_b32_e64 v74, 0, v74, s[40:41]
	v_cndmask_b32_e64 v71, 0, v71, s[38:39]
	v_cndmask_b32_e64 v75, 0, v75, s[40:41]
	v_cndmask_b32_e64 v72, 0, v72, s[38:39]
	v_cndmask_b32_e64 v76, 0, v76, s[40:41]
	v_cndmask_b32_e64 v73, 0, v73, s[38:39]
	v_cndmask_b32_e64 v77, 0, v77, s[40:41]
	v_mul_f32_e32 v66, v208, v66
	v_fmac_f32_e32 v66, v204, v70
	v_fmac_f32_e32 v66, v212, v74
	v_mul_f32_e32 v67, v209, v67
	v_fmac_f32_e32 v67, v205, v71
	v_fmac_f32_e32 v67, v213, v75
	v_mul_f32_e32 v68, v210, v68
	v_fmac_f32_e32 v68, v206, v72
	v_fmac_f32_e32 v68, v214, v76
	v_mul_f32_e32 v69, v211, v69
	v_fmac_f32_e32 v69, v207, v73
	v_fmac_f32_e32 v69, v215, v77
	v_fma_f32 v70, v130, v216, v220
	v_fmac_f32_e32 v70, v194, v66
	v_mul_f32_e32 v70, v18, v70
	v_fma_f32 v71, v131, v217, v221
	v_fmac_f32_e32 v71, v194, v67
	v_mul_f32_e32 v71, v19, v71
	v_fma_f32 v72, v132, v218, v222
	v_fmac_f32_e32 v72, v194, v68
	v_mul_f32_e32 v72, v20, v72
	v_fma_f32 v73, v133, v219, v223
	v_fmac_f32_e32 v73, v194, v69
	v_mul_f32_e32 v73, v21, v73
	v_cvt_pk_f16_f32 v78, v70, v71
	v_cvt_pk_f16_f32 v79, v72, v73
	global_store_dwordx2 v[200:201], v[78:79], off
	ds_read_b128 v[204:207], v116 offset:64
	ds_read_b128 v[208:211], v116 offset:576
	ds_read_b128 v[212:215], v116 offset:1088
	ds_read_b128 v[216:219], v116 offset:1600
	ds_read_b128 v[220:223], v116 offset:2112
	s_nop 0
	s_waitcnt lgkmcnt(5)
	v_cvt_f32_f16_e32 v66, v100
	v_cvt_f32_f16_sdwa v67, v100 dst_sel:DWORD dst_unused:UNUSED_PAD src0_sel:WORD_1
	v_cvt_f32_f16_e32 v70, v164
	v_cvt_f32_f16_sdwa v71, v164 dst_sel:DWORD dst_unused:UNUSED_PAD src0_sel:WORD_1
	v_cvt_f32_f16_e32 v74, v180
	v_cvt_f32_f16_sdwa v75, v180 dst_sel:DWORD dst_unused:UNUSED_PAD src0_sel:WORD_1
	v_cvt_f32_f16_e32 v68, v101
	v_cvt_f32_f16_sdwa v69, v101 dst_sel:DWORD dst_unused:UNUSED_PAD src0_sel:WORD_1
	v_cvt_f32_f16_e32 v72, v165
	v_cvt_f32_f16_sdwa v73, v165 dst_sel:DWORD dst_unused:UNUSED_PAD src0_sel:WORD_1
	v_cvt_f32_f16_e32 v76, v181
	v_cvt_f32_f16_sdwa v77, v181 dst_sel:DWORD dst_unused:UNUSED_PAD src0_sel:WORD_1
	v_cndmask_b32_e64 v70, 0, v70, s[38:39]
	v_cndmask_b32_e64 v74, 0, v74, s[40:41]
	v_cndmask_b32_e64 v71, 0, v71, s[38:39]
	v_cndmask_b32_e64 v75, 0, v75, s[40:41]
	v_cndmask_b32_e64 v72, 0, v72, s[38:39]
	v_cndmask_b32_e64 v76, 0, v76, s[40:41]
	v_cndmask_b32_e64 v73, 0, v73, s[38:39]
	v_cndmask_b32_e64 v77, 0, v77, s[40:41]
	v_mul_f32_e32 v66, v230, v66
	v_fmac_f32_e32 v66, v226, v70
	v_fmac_f32_e32 v66, v234, v74
	v_mul_f32_e32 v67, v231, v67
	v_fmac_f32_e32 v67, v227, v71
	v_fmac_f32_e32 v67, v235, v75
	v_mul_f32_e32 v68, v232, v68
	v_fmac_f32_e32 v68, v228, v72
	v_fmac_f32_e32 v68, v236, v76
	v_mul_f32_e32 v69, v233, v69
	v_fmac_f32_e32 v69, v229, v73
	v_fmac_f32_e32 v69, v237, v77
	v_fma_f32 v70, v134, v238, v242
	v_fmac_f32_e32 v70, v194, v66
	v_mul_f32_e32 v70, v22, v70
	v_fma_f32 v71, v135, v239, v243
	v_fmac_f32_e32 v71, v194, v67
	v_mul_f32_e32 v71, v23, v71
	v_fma_f32 v72, v136, v240, v244
	v_fmac_f32_e32 v72, v194, v68
	v_mul_f32_e32 v72, v24, v72
	v_fma_f32 v73, v137, v241, v245
	v_fmac_f32_e32 v73, v194, v69
	v_mul_f32_e32 v73, v25, v73
	v_cvt_pk_f16_f32 v78, v70, v71
	v_cvt_pk_f16_f32 v79, v72, v73
	global_store_dwordx2 v[200:201], v[78:79], off offset:16
	ds_read_b128 v[226:229], v116 offset:96
	ds_read_b128 v[230:233], v116 offset:608
	ds_read_b128 v[234:237], v116 offset:1120
	ds_read_b128 v[238:241], v116 offset:1632
	ds_read_b128 v[242:245], v116 offset:2144
	s_nop 0
	s_waitcnt lgkmcnt(5)
	v_cvt_f32_f16_e32 v66, v102
	v_cvt_f32_f16_sdwa v67, v102 dst_sel:DWORD dst_unused:UNUSED_PAD src0_sel:WORD_1
	v_cvt_f32_f16_e32 v70, v166
	v_cvt_f32_f16_sdwa v71, v166 dst_sel:DWORD dst_unused:UNUSED_PAD src0_sel:WORD_1
	v_cvt_f32_f16_e32 v74, v182
	v_cvt_f32_f16_sdwa v75, v182 dst_sel:DWORD dst_unused:UNUSED_PAD src0_sel:WORD_1
	v_cvt_f32_f16_e32 v68, v103
	v_cvt_f32_f16_sdwa v69, v103 dst_sel:DWORD dst_unused:UNUSED_PAD src0_sel:WORD_1
	v_cvt_f32_f16_e32 v72, v167
	v_cvt_f32_f16_sdwa v73, v167 dst_sel:DWORD dst_unused:UNUSED_PAD src0_sel:WORD_1
	v_cvt_f32_f16_e32 v76, v183
	v_cvt_f32_f16_sdwa v77, v183 dst_sel:DWORD dst_unused:UNUSED_PAD src0_sel:WORD_1
	v_cndmask_b32_e64 v70, 0, v70, s[38:39]
	v_cndmask_b32_e64 v74, 0, v74, s[40:41]
	v_cndmask_b32_e64 v71, 0, v71, s[38:39]
	v_cndmask_b32_e64 v75, 0, v75, s[40:41]
	v_cndmask_b32_e64 v72, 0, v72, s[38:39]
	v_cndmask_b32_e64 v76, 0, v76, s[40:41]
	v_cndmask_b32_e64 v73, 0, v73, s[38:39]
	v_cndmask_b32_e64 v77, 0, v77, s[40:41]
	v_mul_f32_e32 v66, v208, v66
	v_fmac_f32_e32 v66, v204, v70
	v_fmac_f32_e32 v66, v212, v74
	v_mul_f32_e32 v67, v209, v67
	v_fmac_f32_e32 v67, v205, v71
	v_fmac_f32_e32 v67, v213, v75
	v_mul_f32_e32 v68, v210, v68
	v_fmac_f32_e32 v68, v206, v72
	v_fmac_f32_e32 v68, v214, v76
	v_mul_f32_e32 v69, v211, v69
	v_fmac_f32_e32 v69, v207, v73
	v_fmac_f32_e32 v69, v215, v77
	v_fma_f32 v70, v138, v216, v220
	v_fmac_f32_e32 v70, v194, v66
	v_mul_f32_e32 v70, v26, v70
	v_fma_f32 v71, v139, v217, v221
	v_fmac_f32_e32 v71, v194, v67
	v_mul_f32_e32 v71, v27, v71
	v_fma_f32 v72, v140, v218, v222
	v_fmac_f32_e32 v72, v194, v68
	v_mul_f32_e32 v72, v28, v72
	v_fma_f32 v73, v141, v219, v223
	v_fmac_f32_e32 v73, v194, v69
	v_mul_f32_e32 v73, v29, v73
	v_cvt_pk_f16_f32 v78, v70, v71
	v_cvt_pk_f16_f32 v79, v72, v73
	global_store_dwordx2 v[200:201], v[78:79], off offset:32
	ds_read_b128 v[204:207], v116 offset:128
	ds_read_b128 v[208:211], v116 offset:640
	ds_read_b128 v[212:215], v116 offset:1152
	ds_read_b128 v[216:219], v116 offset:1664
	ds_read_b128 v[220:223], v116 offset:2176
	s_nop 0
	s_waitcnt lgkmcnt(5)
; #define L(ph, l, hf) hipLaunchKernelGGL(k_phase<ph>, dim3(G), dim3(256), 0, stream, p, l, hf)
; DI void phase_post(const P& p, int l, char* smem) {
;     ...
; #pragma unroll
;       for (int mi = 0; mi < 2; ++mi)
; #pragma unroll
;         for (int g = 0; g < 4; ++g) {
;           const int cb_ = m0 + wm * 64 + mi * 32 + 8 * g + 4 * hh;
;           const h16* vp = rkv + (size_t)row * 1536 + 1024 + cb_;
;           h16x4 v1 = *(const h16x4*)vp, v0, v2;
;           v0.x = v0.y = v0.z = v0.w = (h16)0.f; v2 = v0;
;           if (pos > 0) v0 = *(const h16x4*)(vp - 1536);
;           if (pos < L - 1) v2 = *(const h16x4*)(vp + 1536);
;           h16x4 o;
; #pragma unroll
;           for (int e = 0; e < 4; ++e) {
;             const int cc = cb_ + e;
;             const float vv = cvp[cc] * (float)v0[e] + cvp[1536 + cc] * (float)v1[e] + cvp[3072 + cc] * (float)v2[e];
;             const float val = ((y[mi][4 * g + e] - mean) * rstd * lng[cc] + lnb[cc] + bsum * vv) * acc[mi][ni][4 * g + e];
;             o[e] = (h16)val;
;           }
;           *(h16x4*)(rkv + (size_t)row * 1536 + cb_) = o;
;         }
	v_cvt_f32_f16_e32 v66, v104
	v_cvt_f32_f16_sdwa v67, v104 dst_sel:DWORD dst_unused:UNUSED_PAD src0_sel:WORD_1
	v_cvt_f32_f16_e32 v70, v168
	v_cvt_f32_f16_sdwa v71, v168 dst_sel:DWORD dst_unused:UNUSED_PAD src0_sel:WORD_1
	v_cvt_f32_f16_e32 v74, v184
	v_cvt_f32_f16_sdwa v75, v184 dst_sel:DWORD dst_unused:UNUSED_PAD src0_sel:WORD_1
	v_cvt_f32_f16_e32 v68, v105
	v_cvt_f32_f16_sdwa v69, v105 dst_sel:DWORD dst_unused:UNUSED_PAD src0_sel:WORD_1
	v_cvt_f32_f16_e32 v72, v169
	v_cvt_f32_f16_sdwa v73, v169 dst_sel:DWORD dst_unused:UNUSED_PAD src0_sel:WORD_1
	v_cvt_f32_f16_e32 v76, v185
	v_cvt_f32_f16_sdwa v77, v185 dst_sel:DWORD dst_unused:UNUSED_PAD src0_sel:WORD_1
	v_cndmask_b32_e64 v70, 0, v70, s[38:39]
	v_cndmask_b32_e64 v74, 0, v74, s[40:41]
	v_cndmask_b32_e64 v71, 0, v71, s[38:39]
	v_cndmask_b32_e64 v75, 0, v75, s[40:41]
	v_cndmask_b32_e64 v72, 0, v72, s[38:39]
	v_cndmask_b32_e64 v76, 0, v76, s[40:41]
	v_cndmask_b32_e64 v73, 0, v73, s[38:39]
	v_cndmask_b32_e64 v77, 0, v77, s[40:41]
	v_mul_f32_e32 v66, v230, v66
	v_fmac_f32_e32 v66, v226, v70
	v_fmac_f32_e32 v66, v234, v74
	v_mul_f32_e32 v67, v231, v67
	v_fmac_f32_e32 v67, v227, v71
	v_fmac_f32_e32 v67, v235, v75
	v_mul_f32_e32 v68, v232, v68
	v_fmac_f32_e32 v68, v228, v72
	v_fmac_f32_e32 v68, v236, v76
	v_mul_f32_e32 v69, v233, v69
	v_fmac_f32_e32 v69, v229, v73
	v_fmac_f32_e32 v69, v237, v77
	v_fma_f32 v70, v142, v238, v242
	v_fmac_f32_e32 v70, v194, v66
	v_mul_f32_e32 v70, v30, v70
	v_fma_f32 v71, v143, v239, v243
	v_fmac_f32_e32 v71, v194, v67
	v_mul_f32_e32 v71, v31, v71
	v_fma_f32 v72, v144, v240, v244
	v_fmac_f32_e32 v72, v194, v68
	v_mul_f32_e32 v72, v32, v72
	v_fma_f32 v73, v145, v241, v245
	v_fmac_f32_e32 v73, v194, v69
	v_mul_f32_e32 v73, v33, v73
	v_cvt_pk_f16_f32 v78, v70, v71
	v_cvt_pk_f16_f32 v79, v72, v73
	global_store_dwordx2 v[200:201], v[78:79], off offset:48
	ds_read_b128 v[226:229], v116 offset:160
	ds_read_b128 v[230:233], v116 offset:672
	ds_read_b128 v[234:237], v116 offset:1184
	ds_read_b128 v[238:241], v116 offset:1696
	ds_read_b128 v[242:245], v116 offset:2208
	s_nop 0
	s_waitcnt lgkmcnt(5)
	v_cvt_f32_f16_e32 v66, v106
	v_cvt_f32_f16_sdwa v67, v106 dst_sel:DWORD dst_unused:UNUSED_PAD src0_sel:WORD_1
	v_cvt_f32_f16_e32 v70, v170
	v_cvt_f32_f16_sdwa v71, v170 dst_sel:DWORD dst_unused:UNUSED_PAD src0_sel:WORD_1
	v_cvt_f32_f16_e32 v74, v186
	v_cvt_f32_f16_sdwa v75, v186 dst_sel:DWORD dst_unused:UNUSED_PAD src0_sel:WORD_1
	v_cvt_f32_f16_e32 v68, v107
	v_cvt_f32_f16_sdwa v69, v107 dst_sel:DWORD dst_unused:UNUSED_PAD src0_sel:WORD_1
	v_cvt_f32_f16_e32 v72, v171
	v_cvt_f32_f16_sdwa v73, v171 dst_sel:DWORD dst_unused:UNUSED_PAD src0_sel:WORD_1
	v_cvt_f32_f16_e32 v76, v187
	v_cvt_f32_f16_sdwa v77, v187 dst_sel:DWORD dst_unused:UNUSED_PAD src0_sel:WORD_1
	v_cndmask_b32_e64 v70, 0, v70, s[38:39]
	v_cndmask_b32_e64 v74, 0, v74, s[40:41]
	v_cndmask_b32_e64 v71, 0, v71, s[38:39]
	v_cndmask_b32_e64 v75, 0, v75, s[40:41]
	v_cndmask_b32_e64 v72, 0, v72, s[38:39]
	v_cndmask_b32_e64 v76, 0, v76, s[40:41]
	v_cndmask_b32_e64 v73, 0, v73, s[38:39]
	v_cndmask_b32_e64 v77, 0, v77, s[40:41]
	v_mul_f32_e32 v66, v208, v66
	v_fmac_f32_e32 v66, v204, v70
	v_fmac_f32_e32 v66, v212, v74
	v_mul_f32_e32 v67, v209, v67
	v_fmac_f32_e32 v67, v205, v71
	v_fmac_f32_e32 v67, v213, v75
	v_mul_f32_e32 v68, v210, v68
	v_fmac_f32_e32 v68, v206, v72
	v_fmac_f32_e32 v68, v214, v76
	v_mul_f32_e32 v69, v211, v69
	v_fmac_f32_e32 v69, v207, v73
	v_fmac_f32_e32 v69, v215, v77
	v_fma_f32 v70, v146, v216, v220
	v_fmac_f32_e32 v70, v194, v66
	v_mul_f32_e32 v70, v2, v70
	v_fma_f32 v71, v147, v217, v221
	v_fmac_f32_e32 v71, v194, v67
	v_mul_f32_e32 v71, v3, v71
	v_fma_f32 v72, v148, v218, v222
	v_fmac_f32_e32 v72, v194, v68
	v_mul_f32_e32 v72, v4, v72
	v_fma_f32 v73, v149, v219, v223
	v_fmac_f32_e32 v73, v194, v69
	v_mul_f32_e32 v73, v5, v73
	v_cvt_pk_f16_f32 v78, v70, v71
	v_cvt_pk_f16_f32 v79, v72, v73
	global_store_dwordx2 v[200:201], v[78:79], off offset:64
	ds_read_b128 v[204:207], v116 offset:192
	ds_read_b128 v[208:211], v116 offset:704
	ds_read_b128 v[212:215], v116 offset:1216
	ds_read_b128 v[216:219], v116 offset:1728
	ds_read_b128 v[220:223], v116 offset:2240
	s_nop 0
	s_waitcnt lgkmcnt(5)
; DI int BIDX() { int b = blockIdx.x; asm volatile("" : "+s"(b)); return b; }
; DI void phase_post(const P& p, int l, char* smem) {
;     ...
;   for (int t = BIDX(); t < nt; t += gridDim.x) {
;     const int m0 = (t & 3) * 128, n0 = (t >> 2) * 128;
;     f32x16 acc[2][2];
;     zero_acc(acc);
;     gemm_tile_deep(W + (size_t)m0 * 128, 128, lora + (size_t)n0 * 384 + 256, 384, 128, acc, (h16*)smem);
;     const int head = (m0 + wm * 64) >> 6;
; #pragma unroll
;     for (int ni = 0; ni < 2; ++ni) {
;       const int row = n0 + wn * 64 + ni * 32 + (lane & 31);
;       const bool lat = row < TL;
;       const int pos = lat ? (row & 4095) : ((row - TL) & 255);
;       const int L = lat ? 4096 : 256;
;       float y[2][16];
;       float sum = 0.f;
; #pragma unroll
;       for (int mi = 0; mi < 2; ++mi)
; #pragma unroll
;         for (int g = 0; g < 4; ++g) {
;           const int cb_ = m0 + wm * 64 + mi * 32 + 8 * g + 4 * hh;
;           h16x4 f = *(const h16x4*)(sof + (size_t)row * 512 + cb_), bk = *(const h16x4*)(sob + (size_t)row * 512 + cb_);
;           y[mi][4 * g + 0] = (float)f.x + (float)bk.x; y[mi][4 * g + 1] = (float)f.y + (float)bk.y;
;           y[mi][4 * g + 2] = (float)f.z + (float)bk.z; y[mi][4 * g + 3] = (float)f.w + (float)bk.w;
;           sum += y[mi][4 * g] + y[mi][4 * g + 1] + y[mi][4 * g + 2] + y[mi][4 * g + 3];
;         }
;       sum += shx(sum, 32);
;       const float mean = sum * (1.f / 64.f);
;       float vs = 0.f;
; #pragma unroll
;       for (int mi = 0; mi < 2; ++mi)
; #pragma unroll
;         for (int i = 0; i < 16; ++i) { const float dlt = y[mi][i] - mean; vs += dlt * dlt; }
;       vs += shx(vs, 32);
;       const float rstd = rsqrtf(vs * (1.f / 64.f) + 64e-5f);
;       const float bsum = bs[(size_t)row * 8 + head] + bs[((size_t)TA + row) * 8 + head];
; #pragma unroll
;       for (int mi = 0; mi < 2; ++mi)
; #pragma unroll
;         for (int g = 0; g < 4; ++g) {
;           const int cb_ = m0 + wm * 64 + mi * 32 + 8 * g + 4 * hh;
;           const h16* vp = rkv + (size_t)row * 1536 + 1024 + cb_;
;           h16x4 v1 = *(const h16x4*)vp, v0, v2;
;           v0.x = v0.y = v0.z = v0.w = (h16)0.f; v2 = v0;
;           if (pos > 0) v0 = *(const h16x4*)(vp - 1536);
;           if (pos < L - 1) v2 = *(const h16x4*)(vp + 1536);
;           h16x4 o;
; #pragma unroll
;           for (int e = 0; e < 4; ++e) {
;             const int cc = cb_ + e;
	v_cvt_f32_f16_e32 v66, v108
	v_cvt_f32_f16_sdwa v67, v108 dst_sel:DWORD dst_unused:UNUSED_PAD src0_sel:WORD_1
	v_cvt_f32_f16_e32 v70, v172
	v_cvt_f32_f16_sdwa v71, v172 dst_sel:DWORD dst_unused:UNUSED_PAD src0_sel:WORD_1
	v_cvt_f32_f16_e32 v74, v188
	v_cvt_f32_f16_sdwa v75, v188 dst_sel:DWORD dst_unused:UNUSED_PAD src0_sel:WORD_1
	v_cvt_f32_f16_e32 v68, v109
	v_cvt_f32_f16_sdwa v69, v109 dst_sel:DWORD dst_unused:UNUSED_PAD src0_sel:WORD_1
	v_cvt_f32_f16_e32 v72, v173
	v_cvt_f32_f16_sdwa v73, v173 dst_sel:DWORD dst_unused:UNUSED_PAD src0_sel:WORD_1
	v_cvt_f32_f16_e32 v76, v189
	v_cvt_f32_f16_sdwa v77, v189 dst_sel:DWORD dst_unused:UNUSED_PAD src0_sel:WORD_1
	v_cndmask_b32_e64 v70, 0, v70, s[38:39]
	v_cndmask_b32_e64 v74, 0, v74, s[40:41]
	v_cndmask_b32_e64 v71, 0, v71, s[38:39]
	v_cndmask_b32_e64 v75, 0, v75, s[40:41]
	v_cndmask_b32_e64 v72, 0, v72, s[38:39]
	v_cndmask_b32_e64 v76, 0, v76, s[40:41]
	v_cndmask_b32_e64 v73, 0, v73, s[38:39]
	v_cndmask_b32_e64 v77, 0, v77, s[40:41]
	v_mul_f32_e32 v66, v230, v66
	v_fmac_f32_e32 v66, v226, v70
	v_fmac_f32_e32 v66, v234, v74
	v_mul_f32_e32 v67, v231, v67
	v_fmac_f32_e32 v67, v227, v71
	v_fmac_f32_e32 v67, v235, v75
	v_mul_f32_e32 v68, v232, v68
	v_fmac_f32_e32 v68, v228, v72
	v_fmac_f32_e32 v68, v236, v76
	v_mul_f32_e32 v69, v233, v69
	v_fmac_f32_e32 v69, v229, v73
	v_fmac_f32_e32 v69, v237, v77
	v_fma_f32 v70, v150, v238, v242
	v_fmac_f32_e32 v70, v194, v66
	v_mul_f32_e32 v70, v6, v70
	v_fma_f32 v71, v151, v239, v243
	v_fmac_f32_e32 v71, v194, v67
	v_mul_f32_e32 v71, v7, v71
	v_fma_f32 v72, v152, v240, v244
	v_fmac_f32_e32 v72, v194, v68
	v_mul_f32_e32 v72, v8, v72
	v_fma_f32 v73, v153, v241, v245
	v_fmac_f32_e32 v73, v194, v69
	v_mul_f32_e32 v73, v9, v73
	v_cvt_pk_f16_f32 v78, v70, v71
	v_cvt_pk_f16_f32 v79, v72, v73
	global_store_dwordx2 v[200:201], v[78:79], off offset:80
	ds_read_b128 v[226:229], v116 offset:224
	ds_read_b128 v[230:233], v116 offset:736
	ds_read_b128 v[234:237], v116 offset:1248
	ds_read_b128 v[238:241], v116 offset:1760
	ds_read_b128 v[242:245], v116 offset:2272
	s_nop 0
	s_waitcnt lgkmcnt(5)
	v_cvt_f32_f16_e32 v66, v110
	v_cvt_f32_f16_sdwa v67, v110 dst_sel:DWORD dst_unused:UNUSED_PAD src0_sel:WORD_1
	v_cvt_f32_f16_e32 v70, v174
	v_cvt_f32_f16_sdwa v71, v174 dst_sel:DWORD dst_unused:UNUSED_PAD src0_sel:WORD_1
	v_cvt_f32_f16_e32 v74, v190
	v_cvt_f32_f16_sdwa v75, v190 dst_sel:DWORD dst_unused:UNUSED_PAD src0_sel:WORD_1
	v_cvt_f32_f16_e32 v68, v111
	v_cvt_f32_f16_sdwa v69, v111 dst_sel:DWORD dst_unused:UNUSED_PAD src0_sel:WORD_1
	v_cvt_f32_f16_e32 v72, v175
	v_cvt_f32_f16_sdwa v73, v175 dst_sel:DWORD dst_unused:UNUSED_PAD src0_sel:WORD_1
	v_cvt_f32_f16_e32 v76, v191
	v_cvt_f32_f16_sdwa v77, v191 dst_sel:DWORD dst_unused:UNUSED_PAD src0_sel:WORD_1
	v_cndmask_b32_e64 v70, 0, v70, s[38:39]
	v_cndmask_b32_e64 v74, 0, v74, s[40:41]
	v_cndmask_b32_e64 v71, 0, v71, s[38:39]
	v_cndmask_b32_e64 v75, 0, v75, s[40:41]
	v_cndmask_b32_e64 v72, 0, v72, s[38:39]
	v_cndmask_b32_e64 v76, 0, v76, s[40:41]
	v_cndmask_b32_e64 v73, 0, v73, s[38:39]
	v_cndmask_b32_e64 v77, 0, v77, s[40:41]
	v_mul_f32_e32 v66, v208, v66
	v_fmac_f32_e32 v66, v204, v70
	v_fmac_f32_e32 v66, v212, v74
	v_mul_f32_e32 v67, v209, v67
	v_fmac_f32_e32 v67, v205, v71
	v_fmac_f32_e32 v67, v213, v75
	v_mul_f32_e32 v68, v210, v68
	v_fmac_f32_e32 v68, v206, v72
	v_fmac_f32_e32 v68, v214, v76
	v_mul_f32_e32 v69, v211, v69
	v_fmac_f32_e32 v69, v207, v73
	v_fmac_f32_e32 v69, v215, v77
	v_fma_f32 v70, v154, v216, v220
	v_fmac_f32_e32 v70, v194, v66
	v_mul_f32_e32 v70, v10, v70
	v_fma_f32 v71, v155, v217, v221
	v_fmac_f32_e32 v71, v194, v67
	v_mul_f32_e32 v71, v11, v71
	v_fma_f32 v72, v156, v218, v222
	v_fmac_f32_e32 v72, v194, v68
	v_mul_f32_e32 v72, v12, v72
	v_fma_f32 v73, v157, v219, v223
	v_fmac_f32_e32 v73, v194, v69
	v_mul_f32_e32 v73, v13, v73
	v_cvt_pk_f16_f32 v78, v70, v71
	v_cvt_pk_f16_f32 v79, v72, v73
	global_store_dwordx2 v[200:201], v[78:79], off offset:96
	s_nop 0
	s_waitcnt lgkmcnt(0)
	v_cvt_f32_f16_e32 v66, v112
	v_cvt_f32_f16_sdwa v67, v112 dst_sel:DWORD dst_unused:UNUSED_PAD src0_sel:WORD_1
	v_cvt_f32_f16_e32 v70, v176
	v_cvt_f32_f16_sdwa v71, v176 dst_sel:DWORD dst_unused:UNUSED_PAD src0_sel:WORD_1
	v_cvt_f32_f16_e32 v74, v192
	v_cvt_f32_f16_sdwa v75, v192 dst_sel:DWORD dst_unused:UNUSED_PAD src0_sel:WORD_1
	v_cvt_f32_f16_e32 v68, v113
	v_cvt_f32_f16_sdwa v69, v113 dst_sel:DWORD dst_unused:UNUSED_PAD src0_sel:WORD_1
	v_cvt_f32_f16_e32 v72, v177
	v_cvt_f32_f16_sdwa v73, v177 dst_sel:DWORD dst_unused:UNUSED_PAD src0_sel:WORD_1
	v_cvt_f32_f16_e32 v76, v193
	v_cvt_f32_f16_sdwa v77, v193 dst_sel:DWORD dst_unused:UNUSED_PAD src0_sel:WORD_1
	v_cndmask_b32_e64 v70, 0, v70, s[38:39]
	v_cndmask_b32_e64 v74, 0, v74, s[40:41]
	v_cndmask_b32_e64 v71, 0, v71, s[38:39]
	v_cndmask_b32_e64 v75, 0, v75, s[40:41]
	v_cndmask_b32_e64 v72, 0, v72, s[38:39]
	v_cndmask_b32_e64 v76, 0, v76, s[40:41]
	v_cndmask_b32_e64 v73, 0, v73, s[38:39]
	v_cndmask_b32_e64 v77, 0, v77, s[40:41]
	v_mul_f32_e32 v66, v230, v66
	v_fmac_f32_e32 v66, v226, v70
	v_fmac_f32_e32 v66, v234, v74
	v_mul_f32_e32 v67, v231, v67
	v_fmac_f32_e32 v67, v227, v71
	v_fmac_f32_e32 v67, v235, v75
	v_mul_f32_e32 v68, v232, v68
	v_fmac_f32_e32 v68, v228, v72
	v_fmac_f32_e32 v68, v236, v76
	v_mul_f32_e32 v69, v233, v69
	v_fmac_f32_e32 v69, v229, v73
	v_fmac_f32_e32 v69, v237, v77
	v_fma_f32 v70, v158, v238, v242
	v_fmac_f32_e32 v70, v194, v66
	v_mul_f32_e32 v70, v14, v70
	v_fma_f32 v71, v159, v239, v243
	v_fmac_f32_e32 v71, v194, v67
	v_mul_f32_e32 v71, v15, v71
	v_fma_f32 v72, v160, v240, v244
	v_fmac_f32_e32 v72, v194, v68
	v_mul_f32_e32 v72, v16, v72
	v_fma_f32 v73, v161, v241, v245
	v_fmac_f32_e32 v73, v194, v69
	v_mul_f32_e32 v73, v17, v73
	v_cvt_pk_f16_f32 v78, v70, v71
	v_cvt_pk_f16_f32 v79, v72, v73
	global_store_dwordx2 v[200:201], v[78:79], off offset:112
	v_readlane_b32 s0, v254, 39
	s_add_i32 s50, s50, s0
	v_readlane_b32 s0, v254, 40
	s_add_i32 s19, s19, s72
	s_add_i32 s51, s51, s0
	s_cmp_ge_i32 s19, s18
	s_cbranch_scc1 .LBB0_155
	s_branch .LBB0_123

; __global__ void __launch_bounds__(256, 2) k_mega(P p) {
;   __shared__ __attribute__((aligned(16))) char smem[SMEM_BYTES];
;   cg::grid_group grid = cg::this_grid();
;   __shared__ __attribute__((aligned(16))) unsigned xb_words[4];
	.amdhsa_kernel _Z6k_mega1P
		.amdhsa_group_segment_fixed_size 76304
		.amdhsa_private_segment_fixed_size 0
		.amdhsa_kernarg_size 528
		.amdhsa_user_sgpr_count 2
		.amdhsa_user_sgpr_dispatch_ptr 0
		.amdhsa_user_sgpr_queue_ptr 0
		.amdhsa_user_sgpr_kernarg_segment_ptr 1
		.amdhsa_user_sgpr_dispatch_id 0
		.amdhsa_user_sgpr_kernarg_preload_length 0
		.amdhsa_user_sgpr_kernarg_preload_offset 0
		.amdhsa_user_sgpr_private_segment_size 0
		.amdhsa_uses_dynamic_stack 0
		.amdhsa_enable_private_segment 0
		.amdhsa_system_sgpr_workgroup_id_x 1
		.amdhsa_system_sgpr_workgroup_id_y 0
		.amdhsa_system_sgpr_workgroup_id_z 0
		.amdhsa_system_sgpr_workgroup_info 0
		.amdhsa_system_vgpr_workitem_id 2
		.amdhsa_next_free_vgpr 256
		.amdhsa_next_free_sgpr 100
		.amdhsa_accum_offset 256
		.amdhsa_reserve_vcc 1
		.amdhsa_float_round_mode_32 0
		.amdhsa_float_round_mode_16_64 0
		.amdhsa_float_denorm_mode_32 3
		.amdhsa_float_denorm_mode_16_64 3
		.amdhsa_dx10_clamp 1
		.amdhsa_ieee_mode 1
		.amdhsa_fp16_overflow 0
		.amdhsa_tg_split 0
		.amdhsa_exception_fp_ieee_invalid_op 0
		.amdhsa_exception_fp_denorm_src 0
		.amdhsa_exception_fp_ieee_div_zero 0
		.amdhsa_exception_fp_ieee_overflow 0
		.amdhsa_exception_fp_ieee_underflow 0
		.amdhsa_exception_fp_ieee_inexact 0
		.amdhsa_exception_int_div_zero 0
	.end_amdhsa_kernel

; __global__ void __launch_bounds__(256, 2) k_mega(P p) {
;   __shared__ __attribute__((aligned(16))) char smem[SMEM_BYTES];
;   cg::grid_group grid = cg::this_grid();
;   __shared__ __attribute__((aligned(16))) unsigned xb_words[4];
amdhsa.kernels:
  - .agpr_count:     0
    .args:
      - .offset:         0
        .size:           272
        .value_kind:     by_value
      - .offset:         272
        .size:           4
        .value_kind:     hidden_block_count_x
      - .offset:         276
        .size:           4
        .value_kind:     hidden_block_count_y
      - .offset:         280
        .size:           4
        .value_kind:     hidden_block_count_z
      - .offset:         284
        .size:           2
        .value_kind:     hidden_group_size_x
      - .offset:         286
        .size:           2
        .value_kind:     hidden_group_size_y
      - .offset:         288
        .size:           2
        .value_kind:     hidden_group_size_z
      - .offset:         290
        .size:           2
        .value_kind:     hidden_remainder_x
      - .offset:         292
        .size:           2
        .value_kind:     hidden_remainder_y
      - .offset:         294
        .size:           2
        .value_kind:     hidden_remainder_z
      - .offset:         312
        .size:           8
        .value_kind:     hidden_global_offset_x
      - .offset:         320
        .size:           8
        .value_kind:     hidden_global_offset_y
      - .offset:         328
        .size:           8
        .value_kind:     hidden_global_offset_z
      - .offset:         336
        .size:           2
        .value_kind:     hidden_grid_dims
      - .offset:         360
        .size:           8
        .value_kind:     hidden_multigrid_sync_arg
    .group_segment_fixed_size: 76304
    .kernarg_segment_align: 8
    .kernarg_segment_size: 528
    .language:       OpenCL C
    .language_version:
      - 2
      - 0
    .max_flat_workgroup_size: 256
    .name:           _Z6k_mega1P
    .private_segment_fixed_size: 0
    .sgpr_count:     106
    .sgpr_spill_count: 220
    .symbol:         _Z6k_mega1P.kd
    .uniform_work_group_size: 1
    .uses_dynamic_stack: false
    .vgpr_count:     256
    .vgpr_spill_count: 0
    .wavefront_size: 64
